# s5_y and glu K-loops: half 1 of each workgroup reads the operand tile both halves have in common (A for s5_y, B for glu) from half 0's LDS buffer instead of fetching it again
# speedup vs baseline: 1.1113x; 1.0122x over previous
.LBB0_700:
	s_and_b32 s0, s12, 0xff
	s_mulk_i32 s0, 0xab
	s_lshr_b32 s0, s0, 11
	v_readlane_b32 s1, v255, 16
	s_add_i32 s2, s1, s0
	s_mul_i32 s0, s0, 12
	s_sub_i32 s3, s12, s0
	s_lshl_b32 s1, s3, 7
	s_lshl_b32 s0, s2, 9
	s_and_b32 s38, s1, 0x180
	s_or_b32 s0, s0, s38
	s_mulk_i32 s0, 0x600
	s_add_u32 s0, s70, s0
	s_addc_u32 s1, s71, 0
	s_mov_b64 s[22:23], s[0:1]
	s_lshl_b32 s3, s3, 5
	s_mul_i32 s10, s2, 0x180
	s_and_b32 s39, s3, 0x180
	s_add_i32 s10, s10, s39
	v_mov_b32_e32 v46, v235
	s_lshl_b32 s3, s10, 10
	s_add_u32 s40, s68, s3
	v_ashrrev_i32_e32 v32, 3, v46
	v_ashrrev_i32_e32 v33, 31, v32
	s_addc_u32 s41, s69, 0
	s_mov_b64 s[14:15], s[40:41]
	v_lshlrev_b64 v[0:1], 10, v[32:33]
	v_lshlrev_b32_e32 v47, 4, v46
	v_lshl_add_u64 v[0:1], s[40:41], 0, v[0:1]
	v_and_b32_e32 v192, 0x70, v47
	v_lshlrev_b32_e32 v230, 10, v32
	v_or_b32_e32 v230, v230, v192
	v_mul_u32_u24_e32 v231, 0x600, v32
	v_add_u32_e32 v231, v231, v192
	v_lshlrev_b32_e32 v232, 9, v32
	v_or_b32_e32 v232, v232, v192
	v_lshl_add_u64 v[128:129], v[0:1], 0, v[192:193]
	v_mov_b64_e32 v[0:1], s[0:1]
	v_mad_i64_i32 v[0:1], s[0:1], v32, s78, v[0:1]
	v_add_co_u32_e32 v34, vcc, s88, v128
	v_lshl_add_u64 v[130:131], v[0:1], 0, v[192:193]
	s_nop 0
	v_addc_co_u32_e32 v35, vcc, 0, v129, vcc
	v_add_co_u32_e32 v36, vcc, s8, v130
	v_addc_co_u32_e32 v37, vcc, 0, v131, vcc
	v_add_co_u32_e32 v38, vcc, s97, v128
	s_nop 0
	v_addc_co_u32_e32 v39, vcc, 0, v129, vcc
	v_add_co_u32_e32 v40, vcc, s76, v130
	s_nop 0
	v_addc_co_u32_e32 v41, vcc, 0, v131, vcc
	v_add_co_u32_e32 v42, vcc, s9, v130
	s_nop 0
	v_addc_co_u32_e32 v43, vcc, 0, v131, vcc
	v_add_co_u32_e32 v44, vcc, s76, v128
	s_nop 0
	v_addc_co_u32_e32 v45, vcc, 0, v129, vcc
	v_and_b32_e32 v48, 31, v46
	v_lshrrev_b32_e32 v51, 1, v46
	s_mov_b32 s0, 0x1ffffc0
	v_lshrrev_b32_e32 v49, 5, v46
	v_bfe_u32 v50, v46, 5, 1
	v_bfe_u32 v52, v46, 1, 3
	v_lshlrev_b32_e32 v53, 7, v46
	v_lshlrev_b32_e32 v54, 7, v32
	v_xor_b32_e32 v46, v47, v46
	v_and_or_b32 v47, v51, s0, v48
	s_movk_i32 s0, 0x70
	v_and_or_b32 v46, v46, s0, v54
	v_add_u32_e32 v134, s13, v46
	v_readlane_b32 s44, v253, 8
	s_lshl_b32 s0, s10, 9
	v_readlane_b32 s46, v253, 10
	v_readlane_b32 s47, v253, 11
	s_add_u32 s0, s46, s0
	v_lshlrev_b64 v[32:33], 9, v[32:33]
	s_addc_u32 s1, s47, 0
	s_mov_b64 s[80:81], s[0:1]
	v_and_b32_e32 v48, 0x2f80, v53
	v_lshl_add_u64 v[32:33], s[0:1], 0, v[32:33]
	s_mov_b32 s3, 0
	v_lshl_add_u64 v[132:133], v[32:33], 0, v[192:193]
	v_lshl_add_u32 v135, v47, 7, s13
	v_add_u32_e32 v136, s13, v48
	v_readlane_b32 s45, v253, 9
	v_readlane_b32 s48, v253, 12
	v_readlane_b32 s49, v253, 13
	v_readlane_b32 s50, v253, 14
	v_readlane_b32 s51, v253, 15
	v_bitop3_b32 v0, v49, v52, 1 bitop3:0x6c
	v_lshlrev_b32_e32 v137, 4, v0
	v_bitop3_b32 v0, v50, v52, 2 bitop3:0x36
	v_lshlrev_b32_e32 v138, 4, v0
	v_bitop3_b32 v0, v50, v52, 4 bitop3:0x36
	v_lshlrev_b32_e32 v139, 4, v0
	v_bitop3_b32 v0, v50, v52, 6 bitop3:0x36
	v_lshlrev_b32_e32 v140, 4, v0
	s_add_u32 s16, s14, 0x8000
	s_addc_u32 s17, s15, 0
	s_add_u32 s18, s14, 0x10000
	s_addc_u32 s19, s15, 0
	s_add_u32 s20, s14, 0x18000
	s_addc_u32 s21, s15, 0
	s_add_u32 s54, s22, 0xc000
	s_addc_u32 s55, s23, 0
	s_add_u32 s72, s22, 0x18000
	s_addc_u32 s73, s23, 0
	s_add_u32 s74, s22, 0x24000
	s_addc_u32 s75, s23, 0
	s_add_u32 s86, s80, 0x4000
	s_addc_u32 s87, s81, 0
	s_add_u32 s40, s80, 0x8000
	s_addc_u32 s41, s81, 0
	s_add_u32 s44, s80, 0xc000
	s_addc_u32 s45, s81, 0
	s_cmp_lg_u32 s13, 0
	s_cbranch_scc1 .Lsha_s5y_h1
	global_load_dwordx4 v[64:67], v230, s[14:15]
	global_load_dwordx4 v[68:71], v230, s[16:17]
	global_load_dwordx4 v[72:75], v230, s[18:19]
	global_load_dwordx4 v[76:79], v230, s[20:21]
	global_load_dwordx4 v[80:83], v231, s[22:23]
	global_load_dwordx4 v[84:87], v231, s[54:55]
	global_load_dwordx4 v[88:91], v231, s[72:73]
	global_load_dwordx4 v[92:95], v231, s[74:75]
	global_load_dwordx4 v[96:99], v230, s[14:15] offset:128
	global_load_dwordx4 v[100:103], v230, s[16:17] offset:128
	global_load_dwordx4 v[104:107], v230, s[18:19] offset:128
	global_load_dwordx4 v[108:111], v230, s[20:21] offset:128
	global_load_dwordx4 v[112:115], v231, s[22:23] offset:128
	global_load_dwordx4 v[116:119], v231, s[54:55] offset:128
	global_load_dwordx4 v[120:123], v231, s[72:73] offset:128
	global_load_dwordx4 v[124:127], v231, s[74:75] offset:128
	global_load_dwordx4 v[160:163], v230, s[14:15] offset:256
	global_load_dwordx4 v[164:167], v230, s[16:17] offset:256
	global_load_dwordx4 v[168:171], v230, s[18:19] offset:256
	global_load_dwordx4 v[172:175], v230, s[20:21] offset:256
	global_load_dwordx4 v[176:179], v231, s[22:23] offset:256
	global_load_dwordx4 v[180:183], v231, s[54:55] offset:256
	global_load_dwordx4 v[184:187], v231, s[72:73] offset:256
	global_load_dwordx4 v[188:191], v231, s[74:75] offset:256
	global_load_dwordx4 v[196:199], v230, s[14:15] offset:384
	global_load_dwordx4 v[200:203], v230, s[16:17] offset:384
	global_load_dwordx4 v[204:207], v230, s[18:19] offset:384
	global_load_dwordx4 v[208:211], v230, s[20:21] offset:384
	global_load_dwordx4 v[212:215], v231, s[22:23] offset:384
	global_load_dwordx4 v[216:219], v231, s[54:55] offset:384
	global_load_dwordx4 v[220:223], v231, s[72:73] offset:384
	global_load_dwordx4 v[224:227], v231, s[74:75] offset:384
	v_add_u32_e32 v128, v135, v137
	v_add_u32_e32 v132, v136, v137
	v_add_u32_e32 v129, v135, v138
	v_add_u32_e32 v133, v136, v138
	v_add_u32_e32 v130, v135, v139
	v_add_u32_e32 v228, v136, v139
	v_add_u32_e32 v131, v135, v140
	v_add_u32_e32 v229, v136, v140
	v_mov_b32_e32 v0, 0
	v_mov_b32_e32 v1, v0
	v_mov_b32_e32 v2, v0
	v_mov_b32_e32 v3, v0
	v_mov_b32_e32 v4, v0
	v_mov_b32_e32 v5, v0
	v_mov_b32_e32 v6, v0
	v_mov_b32_e32 v7, v0
	v_mov_b32_e32 v8, v0
	v_mov_b32_e32 v9, v0
	v_mov_b32_e32 v10, v0
	v_mov_b32_e32 v11, v0
	v_mov_b32_e32 v12, v0
	v_mov_b32_e32 v13, v0
	v_mov_b32_e32 v14, v0
	v_mov_b32_e32 v15, v0
	v_mov_b32_e32 v16, v0
	v_mov_b32_e32 v17, v0
	v_mov_b32_e32 v18, v0
	v_mov_b32_e32 v19, v0
	v_mov_b32_e32 v20, v0
	v_mov_b32_e32 v21, v0
	v_mov_b32_e32 v22, v0
	v_mov_b32_e32 v23, v0
	v_mov_b32_e32 v24, v0
	v_mov_b32_e32 v25, v0
	v_mov_b32_e32 v26, v0
	v_mov_b32_e32 v27, v0
	v_mov_b32_e32 v28, v0
	v_mov_b32_e32 v29, v0
	v_mov_b32_e32 v30, v0
	v_mov_b32_e32 v31, v0
	v_mov_b32_e32 v32, v0
	v_mov_b32_e32 v33, v0
	v_mov_b32_e32 v34, v0
	v_mov_b32_e32 v35, v0
	v_mov_b32_e32 v36, v0
	v_mov_b32_e32 v37, v0
	v_mov_b32_e32 v38, v0
	v_mov_b32_e32 v39, v0
	v_mov_b32_e32 v40, v0
	v_mov_b32_e32 v41, v0
	v_mov_b32_e32 v42, v0
	v_mov_b32_e32 v43, v0
	v_mov_b32_e32 v44, v0
	v_mov_b32_e32 v45, v0
	v_mov_b32_e32 v46, v0
	v_mov_b32_e32 v47, v0
	v_mov_b32_e32 v48, v0
	v_mov_b32_e32 v49, v0
	v_mov_b32_e32 v50, v0
	v_mov_b32_e32 v51, v0
	v_mov_b32_e32 v52, v0
	v_mov_b32_e32 v53, v0
	v_mov_b32_e32 v54, v0
	v_mov_b32_e32 v55, v0
	v_mov_b32_e32 v56, v0
	v_mov_b32_e32 v57, v0
	v_mov_b32_e32 v58, v0
	v_mov_b32_e32 v59, v0
	v_mov_b32_e32 v60, v0
	v_mov_b32_e32 v61, v0
	v_mov_b32_e32 v62, v0
	v_mov_b32_e32 v63, v0
	s_waitcnt vmcnt(24)
	ds_write_b128 v134, v[64:67]
	ds_write_b128 v134, v[80:83] offset:16384
	ds_write_b128 v134, v[68:71] offset:4096
	ds_write_b128 v134, v[84:87] offset:20480
	ds_write_b128 v134, v[72:75] offset:8192
	ds_write_b128 v134, v[88:91] offset:24576
	ds_write_b128 v134, v[76:79] offset:12288
	ds_write_b128 v134, v[92:95] offset:28672
	s_waitcnt lgkmcnt(0)
	s_barrier
	global_load_dwordx4 v[64:67], v230, s[14:15] offset:512
	global_load_dwordx4 v[68:71], v230, s[16:17] offset:512
	global_load_dwordx4 v[72:75], v230, s[18:19] offset:512
	global_load_dwordx4 v[76:79], v230, s[20:21] offset:512
	global_load_dwordx4 v[80:83], v231, s[22:23] offset:512
	global_load_dwordx4 v[84:87], v231, s[54:55] offset:512
	global_load_dwordx4 v[88:91], v231, s[72:73] offset:512
	global_load_dwordx4 v[92:95], v231, s[74:75] offset:512
	ds_read_b128 v[142:145], v128
	ds_read_b128 v[146:149], v132 offset:16384
	ds_read_b128 v[150:153], v132 offset:20480
	s_waitcnt lgkmcnt(1)
	v_mfma_f32_32x32x16_bf16 v[48:63], v[142:145], v[146:149], v[48:63]
	s_waitcnt lgkmcnt(0)
	v_mfma_f32_32x32x16_bf16 v[32:47], v[142:145], v[150:153], v[32:47]
	ds_read_b128 v[142:145], v128 offset:4096
	s_waitcnt lgkmcnt(0)
	v_mfma_f32_32x32x16_bf16 v[16:31], v[142:145], v[146:149], v[16:31]
	ds_read_b128 v[146:149], v133 offset:16384
	v_mfma_f32_32x32x16_bf16 v[0:15], v[142:145], v[150:153], v[0:15]
	ds_read_b128 v[142:145], v129
	ds_read_b128 v[150:153], v133 offset:20480
	s_waitcnt lgkmcnt(1)
	v_mfma_f32_32x32x16_bf16 v[48:63], v[142:145], v[146:149], v[48:63]
	s_waitcnt lgkmcnt(0)
	v_mfma_f32_32x32x16_bf16 v[32:47], v[142:145], v[150:153], v[32:47]
	ds_read_b128 v[142:145], v129 offset:4096
	s_waitcnt lgkmcnt(0)
	v_mfma_f32_32x32x16_bf16 v[16:31], v[142:145], v[146:149], v[16:31]
	ds_read_b128 v[146:149], v228 offset:16384
	v_mfma_f32_32x32x16_bf16 v[0:15], v[142:145], v[150:153], v[0:15]
	ds_read_b128 v[142:145], v130
	ds_read_b128 v[150:153], v228 offset:20480
	s_waitcnt lgkmcnt(1)
	v_mfma_f32_32x32x16_bf16 v[48:63], v[142:145], v[146:149], v[48:63]
	s_waitcnt lgkmcnt(0)
	v_mfma_f32_32x32x16_bf16 v[32:47], v[142:145], v[150:153], v[32:47]
	ds_read_b128 v[142:145], v130 offset:4096
	s_waitcnt lgkmcnt(0)
	v_mfma_f32_32x32x16_bf16 v[16:31], v[142:145], v[146:149], v[16:31]
	ds_read_b128 v[146:149], v229 offset:16384
	v_mfma_f32_32x32x16_bf16 v[0:15], v[142:145], v[150:153], v[0:15]
	ds_read_b128 v[142:145], v131
	ds_read_b128 v[150:153], v229 offset:20480
	s_waitcnt lgkmcnt(1)
	v_mfma_f32_32x32x16_bf16 v[48:63], v[142:145], v[146:149], v[48:63]
	s_waitcnt lgkmcnt(0)
	v_mfma_f32_32x32x16_bf16 v[32:47], v[142:145], v[150:153], v[32:47]
	ds_read_b128 v[142:145], v131 offset:4096
	s_waitcnt lgkmcnt(0)
	v_mfma_f32_32x32x16_bf16 v[16:31], v[142:145], v[146:149], v[16:31]
	v_mfma_f32_32x32x16_bf16 v[0:15], v[142:145], v[150:153], v[0:15]
	s_waitcnt vmcnt(24)
	ds_write_b128 v134, v[96:99] offset:32768
	ds_write_b128 v134, v[112:115] offset:49152
	ds_write_b128 v134, v[100:103] offset:36864
	ds_write_b128 v134, v[116:119] offset:53248
	ds_write_b128 v134, v[104:107] offset:40960
	ds_write_b128 v134, v[120:123] offset:57344
	ds_write_b128 v134, v[108:111] offset:45056
	ds_write_b128 v134, v[124:127] offset:61440
	s_waitcnt lgkmcnt(0)
	s_barrier
	global_load_dwordx4 v[96:99], v230, s[14:15] offset:640
	global_load_dwordx4 v[100:103], v230, s[16:17] offset:640
	global_load_dwordx4 v[104:107], v230, s[18:19] offset:640
	global_load_dwordx4 v[108:111], v230, s[20:21] offset:640
	global_load_dwordx4 v[112:115], v231, s[22:23] offset:640
	global_load_dwordx4 v[116:119], v231, s[54:55] offset:640
	global_load_dwordx4 v[120:123], v231, s[72:73] offset:640
	global_load_dwordx4 v[124:127], v231, s[74:75] offset:640
	ds_read_b128 v[142:145], v128 offset:32768
	ds_read_b128 v[146:149], v132 offset:49152
	ds_read_b128 v[150:153], v132 offset:53248
	s_waitcnt lgkmcnt(1)
	v_mfma_f32_32x32x16_bf16 v[48:63], v[142:145], v[146:149], v[48:63]
	s_waitcnt lgkmcnt(0)
	v_mfma_f32_32x32x16_bf16 v[32:47], v[142:145], v[150:153], v[32:47]
	ds_read_b128 v[142:145], v128 offset:36864
	s_waitcnt lgkmcnt(0)
	v_mfma_f32_32x32x16_bf16 v[16:31], v[142:145], v[146:149], v[16:31]
	ds_read_b128 v[146:149], v133 offset:49152
	v_mfma_f32_32x32x16_bf16 v[0:15], v[142:145], v[150:153], v[0:15]
	ds_read_b128 v[142:145], v129 offset:32768
	ds_read_b128 v[150:153], v133 offset:53248
	s_waitcnt lgkmcnt(1)
	v_mfma_f32_32x32x16_bf16 v[48:63], v[142:145], v[146:149], v[48:63]
	s_waitcnt lgkmcnt(0)
	v_mfma_f32_32x32x16_bf16 v[32:47], v[142:145], v[150:153], v[32:47]
	ds_read_b128 v[142:145], v129 offset:36864
	s_waitcnt lgkmcnt(0)
	v_mfma_f32_32x32x16_bf16 v[16:31], v[142:145], v[146:149], v[16:31]
	ds_read_b128 v[146:149], v228 offset:49152
	v_mfma_f32_32x32x16_bf16 v[0:15], v[142:145], v[150:153], v[0:15]
	ds_read_b128 v[142:145], v130 offset:32768
	ds_read_b128 v[150:153], v228 offset:53248
	s_waitcnt lgkmcnt(1)
	v_mfma_f32_32x32x16_bf16 v[48:63], v[142:145], v[146:149], v[48:63]
	s_waitcnt lgkmcnt(0)
	v_mfma_f32_32x32x16_bf16 v[32:47], v[142:145], v[150:153], v[32:47]
	ds_read_b128 v[142:145], v130 offset:36864
	s_waitcnt lgkmcnt(0)
	v_mfma_f32_32x32x16_bf16 v[16:31], v[142:145], v[146:149], v[16:31]
	ds_read_b128 v[146:149], v229 offset:49152
	v_mfma_f32_32x32x16_bf16 v[0:15], v[142:145], v[150:153], v[0:15]
	ds_read_b128 v[142:145], v131 offset:32768
	ds_read_b128 v[150:153], v229 offset:53248
	s_waitcnt lgkmcnt(1)
	v_mfma_f32_32x32x16_bf16 v[48:63], v[142:145], v[146:149], v[48:63]
	s_waitcnt lgkmcnt(0)
	v_mfma_f32_32x32x16_bf16 v[32:47], v[142:145], v[150:153], v[32:47]
	ds_read_b128 v[142:145], v131 offset:36864
	s_waitcnt lgkmcnt(0)
	v_mfma_f32_32x32x16_bf16 v[16:31], v[142:145], v[146:149], v[16:31]
	v_mfma_f32_32x32x16_bf16 v[0:15], v[142:145], v[150:153], v[0:15]
	s_waitcnt vmcnt(24)
	ds_write_b128 v134, v[160:163]
	ds_write_b128 v134, v[176:179] offset:16384
	ds_write_b128 v134, v[164:167] offset:4096
	ds_write_b128 v134, v[180:183] offset:20480
	ds_write_b128 v134, v[168:171] offset:8192
	ds_write_b128 v134, v[184:187] offset:24576
	ds_write_b128 v134, v[172:175] offset:12288
	ds_write_b128 v134, v[188:191] offset:28672
	s_waitcnt lgkmcnt(0)
	s_barrier
	global_load_dwordx4 v[160:163], v230, s[14:15] offset:768
	global_load_dwordx4 v[164:167], v230, s[16:17] offset:768
	global_load_dwordx4 v[168:171], v230, s[18:19] offset:768
	global_load_dwordx4 v[172:175], v230, s[20:21] offset:768
	global_load_dwordx4 v[176:179], v231, s[22:23] offset:768
	global_load_dwordx4 v[180:183], v231, s[54:55] offset:768
	global_load_dwordx4 v[184:187], v231, s[72:73] offset:768
	global_load_dwordx4 v[188:191], v231, s[74:75] offset:768
	ds_read_b128 v[142:145], v128
	ds_read_b128 v[146:149], v132 offset:16384
	ds_read_b128 v[150:153], v132 offset:20480
	s_waitcnt lgkmcnt(1)
	v_mfma_f32_32x32x16_bf16 v[48:63], v[142:145], v[146:149], v[48:63]
	s_waitcnt lgkmcnt(0)
	v_mfma_f32_32x32x16_bf16 v[32:47], v[142:145], v[150:153], v[32:47]
	ds_read_b128 v[142:145], v128 offset:4096
	s_waitcnt lgkmcnt(0)
	v_mfma_f32_32x32x16_bf16 v[16:31], v[142:145], v[146:149], v[16:31]
	ds_read_b128 v[146:149], v133 offset:16384
	v_mfma_f32_32x32x16_bf16 v[0:15], v[142:145], v[150:153], v[0:15]
	ds_read_b128 v[142:145], v129
	ds_read_b128 v[150:153], v133 offset:20480
	s_waitcnt lgkmcnt(1)
	v_mfma_f32_32x32x16_bf16 v[48:63], v[142:145], v[146:149], v[48:63]
	s_waitcnt lgkmcnt(0)
	v_mfma_f32_32x32x16_bf16 v[32:47], v[142:145], v[150:153], v[32:47]
	ds_read_b128 v[142:145], v129 offset:4096
	s_waitcnt lgkmcnt(0)
	v_mfma_f32_32x32x16_bf16 v[16:31], v[142:145], v[146:149], v[16:31]
	ds_read_b128 v[146:149], v228 offset:16384
	v_mfma_f32_32x32x16_bf16 v[0:15], v[142:145], v[150:153], v[0:15]
	ds_read_b128 v[142:145], v130
	ds_read_b128 v[150:153], v228 offset:20480
	s_waitcnt lgkmcnt(1)
	v_mfma_f32_32x32x16_bf16 v[48:63], v[142:145], v[146:149], v[48:63]
	s_waitcnt lgkmcnt(0)
	v_mfma_f32_32x32x16_bf16 v[32:47], v[142:145], v[150:153], v[32:47]
	ds_read_b128 v[142:145], v130 offset:4096
	s_waitcnt lgkmcnt(0)
	v_mfma_f32_32x32x16_bf16 v[16:31], v[142:145], v[146:149], v[16:31]
	ds_read_b128 v[146:149], v229 offset:16384
	v_mfma_f32_32x32x16_bf16 v[0:15], v[142:145], v[150:153], v[0:15]
	ds_read_b128 v[142:145], v131
	ds_read_b128 v[150:153], v229 offset:20480
	s_waitcnt lgkmcnt(1)
	v_mfma_f32_32x32x16_bf16 v[48:63], v[142:145], v[146:149], v[48:63]
	s_waitcnt lgkmcnt(0)
	v_mfma_f32_32x32x16_bf16 v[32:47], v[142:145], v[150:153], v[32:47]
	ds_read_b128 v[142:145], v131 offset:4096
	s_waitcnt lgkmcnt(0)
	v_mfma_f32_32x32x16_bf16 v[16:31], v[142:145], v[146:149], v[16:31]
	v_mfma_f32_32x32x16_bf16 v[0:15], v[142:145], v[150:153], v[0:15]
	s_waitcnt vmcnt(24)
	ds_write_b128 v134, v[196:199] offset:32768
	ds_write_b128 v134, v[212:215] offset:49152
	ds_write_b128 v134, v[200:203] offset:36864
	ds_write_b128 v134, v[216:219] offset:53248
	ds_write_b128 v134, v[204:207] offset:40960
	ds_write_b128 v134, v[220:223] offset:57344
	ds_write_b128 v134, v[208:211] offset:45056
	ds_write_b128 v134, v[224:227] offset:61440
	s_waitcnt lgkmcnt(0)
	s_barrier
	global_load_dwordx4 v[196:199], v230, s[14:15] offset:896
	global_load_dwordx4 v[200:203], v230, s[16:17] offset:896
	global_load_dwordx4 v[204:207], v230, s[18:19] offset:896
	global_load_dwordx4 v[208:211], v230, s[20:21] offset:896
	global_load_dwordx4 v[212:215], v231, s[22:23] offset:896
	global_load_dwordx4 v[216:219], v231, s[54:55] offset:896
	global_load_dwordx4 v[220:223], v231, s[72:73] offset:896
	global_load_dwordx4 v[224:227], v231, s[74:75] offset:896
	ds_read_b128 v[142:145], v128 offset:32768
	ds_read_b128 v[146:149], v132 offset:49152
	ds_read_b128 v[150:153], v132 offset:53248
	s_waitcnt lgkmcnt(1)
	v_mfma_f32_32x32x16_bf16 v[48:63], v[142:145], v[146:149], v[48:63]
	s_waitcnt lgkmcnt(0)
	v_mfma_f32_32x32x16_bf16 v[32:47], v[142:145], v[150:153], v[32:47]
	ds_read_b128 v[142:145], v128 offset:36864
	s_waitcnt lgkmcnt(0)
	v_mfma_f32_32x32x16_bf16 v[16:31], v[142:145], v[146:149], v[16:31]
	ds_read_b128 v[146:149], v133 offset:49152
	v_mfma_f32_32x32x16_bf16 v[0:15], v[142:145], v[150:153], v[0:15]
	ds_read_b128 v[142:145], v129 offset:32768
	ds_read_b128 v[150:153], v133 offset:53248
	s_waitcnt lgkmcnt(1)
	v_mfma_f32_32x32x16_bf16 v[48:63], v[142:145], v[146:149], v[48:63]
	s_waitcnt lgkmcnt(0)
	v_mfma_f32_32x32x16_bf16 v[32:47], v[142:145], v[150:153], v[32:47]
	ds_read_b128 v[142:145], v129 offset:36864
	s_waitcnt lgkmcnt(0)
	v_mfma_f32_32x32x16_bf16 v[16:31], v[142:145], v[146:149], v[16:31]
	ds_read_b128 v[146:149], v228 offset:49152
	v_mfma_f32_32x32x16_bf16 v[0:15], v[142:145], v[150:153], v[0:15]
	ds_read_b128 v[142:145], v130 offset:32768
	ds_read_b128 v[150:153], v228 offset:53248
	s_waitcnt lgkmcnt(1)
	v_mfma_f32_32x32x16_bf16 v[48:63], v[142:145], v[146:149], v[48:63]
	s_waitcnt lgkmcnt(0)
	v_mfma_f32_32x32x16_bf16 v[32:47], v[142:145], v[150:153], v[32:47]
	ds_read_b128 v[142:145], v130 offset:36864
	s_waitcnt lgkmcnt(0)
	v_mfma_f32_32x32x16_bf16 v[16:31], v[142:145], v[146:149], v[16:31]
	ds_read_b128 v[146:149], v229 offset:49152
	v_mfma_f32_32x32x16_bf16 v[0:15], v[142:145], v[150:153], v[0:15]
	ds_read_b128 v[142:145], v131 offset:32768
	ds_read_b128 v[150:153], v229 offset:53248
	s_waitcnt lgkmcnt(1)
	v_mfma_f32_32x32x16_bf16 v[48:63], v[142:145], v[146:149], v[48:63]
	s_waitcnt lgkmcnt(0)
	v_mfma_f32_32x32x16_bf16 v[32:47], v[142:145], v[150:153], v[32:47]
	ds_read_b128 v[142:145], v131 offset:36864
	s_waitcnt lgkmcnt(0)
	v_mfma_f32_32x32x16_bf16 v[16:31], v[142:145], v[146:149], v[16:31]
	v_mfma_f32_32x32x16_bf16 v[0:15], v[142:145], v[150:153], v[0:15]
	s_waitcnt vmcnt(24)
	ds_write_b128 v134, v[64:67]
	ds_write_b128 v134, v[80:83] offset:16384
	ds_write_b128 v134, v[68:71] offset:4096
	ds_write_b128 v134, v[84:87] offset:20480
	ds_write_b128 v134, v[72:75] offset:8192
	ds_write_b128 v134, v[88:91] offset:24576
	ds_write_b128 v134, v[76:79] offset:12288
	ds_write_b128 v134, v[92:95] offset:28672
	s_waitcnt lgkmcnt(0)
	s_barrier
	global_load_dwordx4 v[64:67], v232, s[80:81]
	global_load_dwordx4 v[68:71], v232, s[86:87]
	global_load_dwordx4 v[72:75], v232, s[40:41]
	global_load_dwordx4 v[76:79], v232, s[44:45]
	global_load_dwordx4 v[80:83], v231, s[22:23] offset:1024
	global_load_dwordx4 v[84:87], v231, s[54:55] offset:1024
	global_load_dwordx4 v[88:91], v231, s[72:73] offset:1024
	global_load_dwordx4 v[92:95], v231, s[74:75] offset:1024
	ds_read_b128 v[142:145], v128
	ds_read_b128 v[146:149], v132 offset:16384
	ds_read_b128 v[150:153], v132 offset:20480
	s_waitcnt lgkmcnt(1)
	v_mfma_f32_32x32x16_bf16 v[48:63], v[142:145], v[146:149], v[48:63]
	s_waitcnt lgkmcnt(0)
	v_mfma_f32_32x32x16_bf16 v[32:47], v[142:145], v[150:153], v[32:47]
	ds_read_b128 v[142:145], v128 offset:4096
	s_waitcnt lgkmcnt(0)
	v_mfma_f32_32x32x16_bf16 v[16:31], v[142:145], v[146:149], v[16:31]
	ds_read_b128 v[146:149], v133 offset:16384
	v_mfma_f32_32x32x16_bf16 v[0:15], v[142:145], v[150:153], v[0:15]
	ds_read_b128 v[142:145], v129
	ds_read_b128 v[150:153], v133 offset:20480
	s_waitcnt lgkmcnt(1)
	v_mfma_f32_32x32x16_bf16 v[48:63], v[142:145], v[146:149], v[48:63]
	s_waitcnt lgkmcnt(0)
	v_mfma_f32_32x32x16_bf16 v[32:47], v[142:145], v[150:153], v[32:47]
	ds_read_b128 v[142:145], v129 offset:4096
	s_waitcnt lgkmcnt(0)
	v_mfma_f32_32x32x16_bf16 v[16:31], v[142:145], v[146:149], v[16:31]
	ds_read_b128 v[146:149], v228 offset:16384
	v_mfma_f32_32x32x16_bf16 v[0:15], v[142:145], v[150:153], v[0:15]
	ds_read_b128 v[142:145], v130
	ds_read_b128 v[150:153], v228 offset:20480
	s_waitcnt lgkmcnt(1)
	v_mfma_f32_32x32x16_bf16 v[48:63], v[142:145], v[146:149], v[48:63]
	s_waitcnt lgkmcnt(0)
	v_mfma_f32_32x32x16_bf16 v[32:47], v[142:145], v[150:153], v[32:47]
	ds_read_b128 v[142:145], v130 offset:4096
	s_waitcnt lgkmcnt(0)
	v_mfma_f32_32x32x16_bf16 v[16:31], v[142:145], v[146:149], v[16:31]
	ds_read_b128 v[146:149], v229 offset:16384
	v_mfma_f32_32x32x16_bf16 v[0:15], v[142:145], v[150:153], v[0:15]
	ds_read_b128 v[142:145], v131
	ds_read_b128 v[150:153], v229 offset:20480
	s_waitcnt lgkmcnt(1)
	v_mfma_f32_32x32x16_bf16 v[48:63], v[142:145], v[146:149], v[48:63]
	s_waitcnt lgkmcnt(0)
	v_mfma_f32_32x32x16_bf16 v[32:47], v[142:145], v[150:153], v[32:47]
	ds_read_b128 v[142:145], v131 offset:4096
	s_waitcnt lgkmcnt(0)
	v_mfma_f32_32x32x16_bf16 v[16:31], v[142:145], v[146:149], v[16:31]
	v_mfma_f32_32x32x16_bf16 v[0:15], v[142:145], v[150:153], v[0:15]
	s_waitcnt vmcnt(24)
	ds_write_b128 v134, v[96:99] offset:32768
	ds_write_b128 v134, v[112:115] offset:49152
	ds_write_b128 v134, v[100:103] offset:36864
	ds_write_b128 v134, v[116:119] offset:53248
	ds_write_b128 v134, v[104:107] offset:40960
	ds_write_b128 v134, v[120:123] offset:57344
	ds_write_b128 v134, v[108:111] offset:45056
	ds_write_b128 v134, v[124:127] offset:61440
	s_waitcnt lgkmcnt(0)
	s_barrier
	global_load_dwordx4 v[96:99], v232, s[80:81] offset:128
	global_load_dwordx4 v[100:103], v232, s[86:87] offset:128
	global_load_dwordx4 v[104:107], v232, s[40:41] offset:128
	global_load_dwordx4 v[108:111], v232, s[44:45] offset:128
	global_load_dwordx4 v[112:115], v231, s[22:23] offset:1152
	global_load_dwordx4 v[116:119], v231, s[54:55] offset:1152
	global_load_dwordx4 v[120:123], v231, s[72:73] offset:1152
	global_load_dwordx4 v[124:127], v231, s[74:75] offset:1152
	ds_read_b128 v[142:145], v128 offset:32768
	ds_read_b128 v[146:149], v132 offset:49152
	ds_read_b128 v[150:153], v132 offset:53248
	s_waitcnt lgkmcnt(1)
	v_mfma_f32_32x32x16_bf16 v[48:63], v[142:145], v[146:149], v[48:63]
	s_waitcnt lgkmcnt(0)
	v_mfma_f32_32x32x16_bf16 v[32:47], v[142:145], v[150:153], v[32:47]
	ds_read_b128 v[142:145], v128 offset:36864
	s_waitcnt lgkmcnt(0)
	v_mfma_f32_32x32x16_bf16 v[16:31], v[142:145], v[146:149], v[16:31]
	ds_read_b128 v[146:149], v133 offset:49152
	v_mfma_f32_32x32x16_bf16 v[0:15], v[142:145], v[150:153], v[0:15]
	ds_read_b128 v[142:145], v129 offset:32768
	ds_read_b128 v[150:153], v133 offset:53248
	s_waitcnt lgkmcnt(1)
	v_mfma_f32_32x32x16_bf16 v[48:63], v[142:145], v[146:149], v[48:63]
	s_waitcnt lgkmcnt(0)
	v_mfma_f32_32x32x16_bf16 v[32:47], v[142:145], v[150:153], v[32:47]
	ds_read_b128 v[142:145], v129 offset:36864
	s_waitcnt lgkmcnt(0)
	v_mfma_f32_32x32x16_bf16 v[16:31], v[142:145], v[146:149], v[16:31]
	ds_read_b128 v[146:149], v228 offset:49152
	v_mfma_f32_32x32x16_bf16 v[0:15], v[142:145], v[150:153], v[0:15]
	ds_read_b128 v[142:145], v130 offset:32768
	ds_read_b128 v[150:153], v228 offset:53248
	s_waitcnt lgkmcnt(1)
	v_mfma_f32_32x32x16_bf16 v[48:63], v[142:145], v[146:149], v[48:63]
	s_waitcnt lgkmcnt(0)
	v_mfma_f32_32x32x16_bf16 v[32:47], v[142:145], v[150:153], v[32:47]
	ds_read_b128 v[142:145], v130 offset:36864
	s_waitcnt lgkmcnt(0)
	v_mfma_f32_32x32x16_bf16 v[16:31], v[142:145], v[146:149], v[16:31]
	ds_read_b128 v[146:149], v229 offset:49152
	v_mfma_f32_32x32x16_bf16 v[0:15], v[142:145], v[150:153], v[0:15]
	ds_read_b128 v[142:145], v131 offset:32768
	ds_read_b128 v[150:153], v229 offset:53248
	s_waitcnt lgkmcnt(1)
	v_mfma_f32_32x32x16_bf16 v[48:63], v[142:145], v[146:149], v[48:63]
	s_waitcnt lgkmcnt(0)
	v_mfma_f32_32x32x16_bf16 v[32:47], v[142:145], v[150:153], v[32:47]
	ds_read_b128 v[142:145], v131 offset:36864
	s_waitcnt lgkmcnt(0)
	v_mfma_f32_32x32x16_bf16 v[16:31], v[142:145], v[146:149], v[16:31]
	v_mfma_f32_32x32x16_bf16 v[0:15], v[142:145], v[150:153], v[0:15]
	s_waitcnt vmcnt(24)
	ds_write_b128 v134, v[160:163]
	ds_write_b128 v134, v[176:179] offset:16384
	ds_write_b128 v134, v[164:167] offset:4096
	ds_write_b128 v134, v[180:183] offset:20480
	ds_write_b128 v134, v[168:171] offset:8192
	ds_write_b128 v134, v[184:187] offset:24576
	ds_write_b128 v134, v[172:175] offset:12288
	ds_write_b128 v134, v[188:191] offset:28672
	s_waitcnt lgkmcnt(0)
	s_barrier
	global_load_dwordx4 v[160:163], v232, s[80:81] offset:256
	global_load_dwordx4 v[164:167], v232, s[86:87] offset:256
	global_load_dwordx4 v[168:171], v232, s[40:41] offset:256
	global_load_dwordx4 v[172:175], v232, s[44:45] offset:256
	global_load_dwordx4 v[176:179], v231, s[22:23] offset:1280
	global_load_dwordx4 v[180:183], v231, s[54:55] offset:1280
	global_load_dwordx4 v[184:187], v231, s[72:73] offset:1280
	global_load_dwordx4 v[188:191], v231, s[74:75] offset:1280
	ds_read_b128 v[142:145], v128
	ds_read_b128 v[146:149], v132 offset:16384
	ds_read_b128 v[150:153], v132 offset:20480
	s_waitcnt lgkmcnt(1)
	v_mfma_f32_32x32x16_bf16 v[48:63], v[142:145], v[146:149], v[48:63]
	s_waitcnt lgkmcnt(0)
	v_mfma_f32_32x32x16_bf16 v[32:47], v[142:145], v[150:153], v[32:47]
	ds_read_b128 v[142:145], v128 offset:4096
	s_waitcnt lgkmcnt(0)
	v_mfma_f32_32x32x16_bf16 v[16:31], v[142:145], v[146:149], v[16:31]
	ds_read_b128 v[146:149], v133 offset:16384
	v_mfma_f32_32x32x16_bf16 v[0:15], v[142:145], v[150:153], v[0:15]
	ds_read_b128 v[142:145], v129
	ds_read_b128 v[150:153], v133 offset:20480
	s_waitcnt lgkmcnt(1)
	v_mfma_f32_32x32x16_bf16 v[48:63], v[142:145], v[146:149], v[48:63]
	s_waitcnt lgkmcnt(0)
	v_mfma_f32_32x32x16_bf16 v[32:47], v[142:145], v[150:153], v[32:47]
	ds_read_b128 v[142:145], v129 offset:4096
	s_waitcnt lgkmcnt(0)
	v_mfma_f32_32x32x16_bf16 v[16:31], v[142:145], v[146:149], v[16:31]
	ds_read_b128 v[146:149], v228 offset:16384
	v_mfma_f32_32x32x16_bf16 v[0:15], v[142:145], v[150:153], v[0:15]
	ds_read_b128 v[142:145], v130
	ds_read_b128 v[150:153], v228 offset:20480
	s_waitcnt lgkmcnt(1)
	v_mfma_f32_32x32x16_bf16 v[48:63], v[142:145], v[146:149], v[48:63]
	s_waitcnt lgkmcnt(0)
	v_mfma_f32_32x32x16_bf16 v[32:47], v[142:145], v[150:153], v[32:47]
	ds_read_b128 v[142:145], v130 offset:4096
	s_waitcnt lgkmcnt(0)
	v_mfma_f32_32x32x16_bf16 v[16:31], v[142:145], v[146:149], v[16:31]
	ds_read_b128 v[146:149], v229 offset:16384
	v_mfma_f32_32x32x16_bf16 v[0:15], v[142:145], v[150:153], v[0:15]
	ds_read_b128 v[142:145], v131
	ds_read_b128 v[150:153], v229 offset:20480
	s_waitcnt lgkmcnt(1)
	v_mfma_f32_32x32x16_bf16 v[48:63], v[142:145], v[146:149], v[48:63]
	s_waitcnt lgkmcnt(0)
	v_mfma_f32_32x32x16_bf16 v[32:47], v[142:145], v[150:153], v[32:47]
	ds_read_b128 v[142:145], v131 offset:4096
	s_waitcnt lgkmcnt(0)
	v_mfma_f32_32x32x16_bf16 v[16:31], v[142:145], v[146:149], v[16:31]
	v_mfma_f32_32x32x16_bf16 v[0:15], v[142:145], v[150:153], v[0:15]
	s_waitcnt vmcnt(24)
	ds_write_b128 v134, v[196:199] offset:32768
	ds_write_b128 v134, v[212:215] offset:49152
	ds_write_b128 v134, v[200:203] offset:36864
	ds_write_b128 v134, v[216:219] offset:53248
	ds_write_b128 v134, v[204:207] offset:40960
	ds_write_b128 v134, v[220:223] offset:57344
	ds_write_b128 v134, v[208:211] offset:45056
	ds_write_b128 v134, v[224:227] offset:61440
	s_waitcnt lgkmcnt(0)
	s_barrier
	global_load_dwordx4 v[196:199], v232, s[80:81] offset:384
	global_load_dwordx4 v[200:203], v232, s[86:87] offset:384
	global_load_dwordx4 v[204:207], v232, s[40:41] offset:384
	global_load_dwordx4 v[208:211], v232, s[44:45] offset:384
	global_load_dwordx4 v[212:215], v231, s[22:23] offset:1408
	global_load_dwordx4 v[216:219], v231, s[54:55] offset:1408
	global_load_dwordx4 v[220:223], v231, s[72:73] offset:1408
	global_load_dwordx4 v[224:227], v231, s[74:75] offset:1408
	ds_read_b128 v[142:145], v128 offset:32768
	ds_read_b128 v[146:149], v132 offset:49152
	ds_read_b128 v[150:153], v132 offset:53248
	s_waitcnt lgkmcnt(1)
	v_mfma_f32_32x32x16_bf16 v[48:63], v[142:145], v[146:149], v[48:63]
	s_waitcnt lgkmcnt(0)
	v_mfma_f32_32x32x16_bf16 v[32:47], v[142:145], v[150:153], v[32:47]
	ds_read_b128 v[142:145], v128 offset:36864
	s_waitcnt lgkmcnt(0)
	v_mfma_f32_32x32x16_bf16 v[16:31], v[142:145], v[146:149], v[16:31]
	ds_read_b128 v[146:149], v133 offset:49152
	v_mfma_f32_32x32x16_bf16 v[0:15], v[142:145], v[150:153], v[0:15]
	ds_read_b128 v[142:145], v129 offset:32768
	ds_read_b128 v[150:153], v133 offset:53248
	s_waitcnt lgkmcnt(1)
	v_mfma_f32_32x32x16_bf16 v[48:63], v[142:145], v[146:149], v[48:63]
	s_waitcnt lgkmcnt(0)
	v_mfma_f32_32x32x16_bf16 v[32:47], v[142:145], v[150:153], v[32:47]
	ds_read_b128 v[142:145], v129 offset:36864
	s_waitcnt lgkmcnt(0)
	v_mfma_f32_32x32x16_bf16 v[16:31], v[142:145], v[146:149], v[16:31]
	ds_read_b128 v[146:149], v228 offset:49152
	v_mfma_f32_32x32x16_bf16 v[0:15], v[142:145], v[150:153], v[0:15]
	ds_read_b128 v[142:145], v130 offset:32768
	ds_read_b128 v[150:153], v228 offset:53248
	s_waitcnt lgkmcnt(1)
	v_mfma_f32_32x32x16_bf16 v[48:63], v[142:145], v[146:149], v[48:63]
	s_waitcnt lgkmcnt(0)
	v_mfma_f32_32x32x16_bf16 v[32:47], v[142:145], v[150:153], v[32:47]
	ds_read_b128 v[142:145], v130 offset:36864
	s_waitcnt lgkmcnt(0)
	v_mfma_f32_32x32x16_bf16 v[16:31], v[142:145], v[146:149], v[16:31]
	ds_read_b128 v[146:149], v229 offset:49152
	v_mfma_f32_32x32x16_bf16 v[0:15], v[142:145], v[150:153], v[0:15]
	ds_read_b128 v[142:145], v131 offset:32768
	ds_read_b128 v[150:153], v229 offset:53248
	s_waitcnt lgkmcnt(1)
	v_mfma_f32_32x32x16_bf16 v[48:63], v[142:145], v[146:149], v[48:63]
	s_waitcnt lgkmcnt(0)
	v_mfma_f32_32x32x16_bf16 v[32:47], v[142:145], v[150:153], v[32:47]
	ds_read_b128 v[142:145], v131 offset:36864
	s_waitcnt lgkmcnt(0)
	v_mfma_f32_32x32x16_bf16 v[16:31], v[142:145], v[146:149], v[16:31]
	v_mfma_f32_32x32x16_bf16 v[0:15], v[142:145], v[150:153], v[0:15]
	s_waitcnt vmcnt(24)
	ds_write_b128 v134, v[64:67]
	ds_write_b128 v134, v[80:83] offset:16384
	ds_write_b128 v134, v[68:71] offset:4096
	ds_write_b128 v134, v[84:87] offset:20480
	ds_write_b128 v134, v[72:75] offset:8192
	ds_write_b128 v134, v[88:91] offset:24576
	ds_write_b128 v134, v[76:79] offset:12288
	ds_write_b128 v134, v[92:95] offset:28672
	s_waitcnt lgkmcnt(0)
	s_barrier
	ds_read_b128 v[142:145], v128
	ds_read_b128 v[146:149], v132 offset:16384
	ds_read_b128 v[150:153], v132 offset:20480
	s_waitcnt lgkmcnt(1)
	v_mfma_f32_32x32x16_bf16 v[48:63], v[142:145], v[146:149], v[48:63]
	s_waitcnt lgkmcnt(0)
	v_mfma_f32_32x32x16_bf16 v[32:47], v[142:145], v[150:153], v[32:47]
	ds_read_b128 v[142:145], v128 offset:4096
	s_waitcnt lgkmcnt(0)
	v_mfma_f32_32x32x16_bf16 v[16:31], v[142:145], v[146:149], v[16:31]
	ds_read_b128 v[146:149], v133 offset:16384
	v_mfma_f32_32x32x16_bf16 v[0:15], v[142:145], v[150:153], v[0:15]
	ds_read_b128 v[142:145], v129
	ds_read_b128 v[150:153], v133 offset:20480
	s_waitcnt lgkmcnt(1)
	v_mfma_f32_32x32x16_bf16 v[48:63], v[142:145], v[146:149], v[48:63]
	s_waitcnt lgkmcnt(0)
	v_mfma_f32_32x32x16_bf16 v[32:47], v[142:145], v[150:153], v[32:47]
	ds_read_b128 v[142:145], v129 offset:4096
	s_waitcnt lgkmcnt(0)
	v_mfma_f32_32x32x16_bf16 v[16:31], v[142:145], v[146:149], v[16:31]
	ds_read_b128 v[146:149], v228 offset:16384
	v_mfma_f32_32x32x16_bf16 v[0:15], v[142:145], v[150:153], v[0:15]
	ds_read_b128 v[142:145], v130
	ds_read_b128 v[150:153], v228 offset:20480
	s_waitcnt lgkmcnt(1)
	v_mfma_f32_32x32x16_bf16 v[48:63], v[142:145], v[146:149], v[48:63]
	s_waitcnt lgkmcnt(0)
	v_mfma_f32_32x32x16_bf16 v[32:47], v[142:145], v[150:153], v[32:47]
	ds_read_b128 v[142:145], v130 offset:4096
	s_waitcnt lgkmcnt(0)
	v_mfma_f32_32x32x16_bf16 v[16:31], v[142:145], v[146:149], v[16:31]
	ds_read_b128 v[146:149], v229 offset:16384
	v_mfma_f32_32x32x16_bf16 v[0:15], v[142:145], v[150:153], v[0:15]
	ds_read_b128 v[142:145], v131
	ds_read_b128 v[150:153], v229 offset:20480
	s_waitcnt lgkmcnt(1)
	v_mfma_f32_32x32x16_bf16 v[48:63], v[142:145], v[146:149], v[48:63]
	s_waitcnt lgkmcnt(0)
	v_mfma_f32_32x32x16_bf16 v[32:47], v[142:145], v[150:153], v[32:47]
	ds_read_b128 v[142:145], v131 offset:4096
	s_waitcnt lgkmcnt(0)
	v_mfma_f32_32x32x16_bf16 v[16:31], v[142:145], v[146:149], v[16:31]
	v_mfma_f32_32x32x16_bf16 v[0:15], v[142:145], v[150:153], v[0:15]
	s_waitcnt vmcnt(16)
	ds_write_b128 v134, v[96:99] offset:32768
	ds_write_b128 v134, v[112:115] offset:49152
	ds_write_b128 v134, v[100:103] offset:36864
	ds_write_b128 v134, v[116:119] offset:53248
	ds_write_b128 v134, v[104:107] offset:40960
	ds_write_b128 v134, v[120:123] offset:57344
	ds_write_b128 v134, v[108:111] offset:45056
	ds_write_b128 v134, v[124:127] offset:61440
	s_waitcnt lgkmcnt(0)
	s_barrier
	ds_read_b128 v[142:145], v128 offset:32768
	ds_read_b128 v[146:149], v132 offset:49152
	ds_read_b128 v[150:153], v132 offset:53248
	s_waitcnt lgkmcnt(1)
	v_mfma_f32_32x32x16_bf16 v[48:63], v[142:145], v[146:149], v[48:63]
	s_waitcnt lgkmcnt(0)
	v_mfma_f32_32x32x16_bf16 v[32:47], v[142:145], v[150:153], v[32:47]
	ds_read_b128 v[142:145], v128 offset:36864
	s_waitcnt lgkmcnt(0)
	v_mfma_f32_32x32x16_bf16 v[16:31], v[142:145], v[146:149], v[16:31]
	ds_read_b128 v[146:149], v133 offset:49152
	v_mfma_f32_32x32x16_bf16 v[0:15], v[142:145], v[150:153], v[0:15]
	ds_read_b128 v[142:145], v129 offset:32768
	ds_read_b128 v[150:153], v133 offset:53248
	s_waitcnt lgkmcnt(1)
	v_mfma_f32_32x32x16_bf16 v[48:63], v[142:145], v[146:149], v[48:63]
	s_waitcnt lgkmcnt(0)
	v_mfma_f32_32x32x16_bf16 v[32:47], v[142:145], v[150:153], v[32:47]
	ds_read_b128 v[142:145], v129 offset:36864
	s_waitcnt lgkmcnt(0)
	v_mfma_f32_32x32x16_bf16 v[16:31], v[142:145], v[146:149], v[16:31]
	ds_read_b128 v[146:149], v228 offset:49152
	v_mfma_f32_32x32x16_bf16 v[0:15], v[142:145], v[150:153], v[0:15]
	ds_read_b128 v[142:145], v130 offset:32768
	ds_read_b128 v[150:153], v228 offset:53248
	s_waitcnt lgkmcnt(1)
	v_mfma_f32_32x32x16_bf16 v[48:63], v[142:145], v[146:149], v[48:63]
	s_waitcnt lgkmcnt(0)
	v_mfma_f32_32x32x16_bf16 v[32:47], v[142:145], v[150:153], v[32:47]
	ds_read_b128 v[142:145], v130 offset:36864
	s_waitcnt lgkmcnt(0)
	v_mfma_f32_32x32x16_bf16 v[16:31], v[142:145], v[146:149], v[16:31]
	ds_read_b128 v[146:149], v229 offset:49152
	v_mfma_f32_32x32x16_bf16 v[0:15], v[142:145], v[150:153], v[0:15]
	ds_read_b128 v[142:145], v131 offset:32768
	ds_read_b128 v[150:153], v229 offset:53248
	s_waitcnt lgkmcnt(1)
	v_mfma_f32_32x32x16_bf16 v[48:63], v[142:145], v[146:149], v[48:63]
	s_waitcnt lgkmcnt(0)
	v_mfma_f32_32x32x16_bf16 v[32:47], v[142:145], v[150:153], v[32:47]
	ds_read_b128 v[142:145], v131 offset:36864
	s_waitcnt lgkmcnt(0)
	v_mfma_f32_32x32x16_bf16 v[16:31], v[142:145], v[146:149], v[16:31]
	v_mfma_f32_32x32x16_bf16 v[0:15], v[142:145], v[150:153], v[0:15]
	s_waitcnt vmcnt(8)
	ds_write_b128 v134, v[160:163]
	ds_write_b128 v134, v[176:179] offset:16384
	ds_write_b128 v134, v[164:167] offset:4096
	ds_write_b128 v134, v[180:183] offset:20480
	ds_write_b128 v134, v[168:171] offset:8192
	ds_write_b128 v134, v[184:187] offset:24576
	ds_write_b128 v134, v[172:175] offset:12288
	ds_write_b128 v134, v[188:191] offset:28672
	s_waitcnt lgkmcnt(0)
	s_barrier
	ds_read_b128 v[142:145], v128
	ds_read_b128 v[146:149], v132 offset:16384
	ds_read_b128 v[150:153], v132 offset:20480
	s_waitcnt lgkmcnt(1)
	v_mfma_f32_32x32x16_bf16 v[48:63], v[142:145], v[146:149], v[48:63]
	s_waitcnt lgkmcnt(0)
	v_mfma_f32_32x32x16_bf16 v[32:47], v[142:145], v[150:153], v[32:47]
	ds_read_b128 v[142:145], v128 offset:4096
	s_waitcnt lgkmcnt(0)
	v_mfma_f32_32x32x16_bf16 v[16:31], v[142:145], v[146:149], v[16:31]
	ds_read_b128 v[146:149], v133 offset:16384
	v_mfma_f32_32x32x16_bf16 v[0:15], v[142:145], v[150:153], v[0:15]
	ds_read_b128 v[142:145], v129
	ds_read_b128 v[150:153], v133 offset:20480
	s_waitcnt lgkmcnt(1)
	v_mfma_f32_32x32x16_bf16 v[48:63], v[142:145], v[146:149], v[48:63]
	s_waitcnt lgkmcnt(0)
	v_mfma_f32_32x32x16_bf16 v[32:47], v[142:145], v[150:153], v[32:47]
	ds_read_b128 v[142:145], v129 offset:4096
	s_waitcnt lgkmcnt(0)
	v_mfma_f32_32x32x16_bf16 v[16:31], v[142:145], v[146:149], v[16:31]
	ds_read_b128 v[146:149], v228 offset:16384
	v_mfma_f32_32x32x16_bf16 v[0:15], v[142:145], v[150:153], v[0:15]
	ds_read_b128 v[142:145], v130
	ds_read_b128 v[150:153], v228 offset:20480
	s_waitcnt lgkmcnt(1)
	v_mfma_f32_32x32x16_bf16 v[48:63], v[142:145], v[146:149], v[48:63]
	s_waitcnt lgkmcnt(0)
	v_mfma_f32_32x32x16_bf16 v[32:47], v[142:145], v[150:153], v[32:47]
	ds_read_b128 v[142:145], v130 offset:4096
	s_waitcnt lgkmcnt(0)
	v_mfma_f32_32x32x16_bf16 v[16:31], v[142:145], v[146:149], v[16:31]
	ds_read_b128 v[146:149], v229 offset:16384
	v_mfma_f32_32x32x16_bf16 v[0:15], v[142:145], v[150:153], v[0:15]
	ds_read_b128 v[142:145], v131
	ds_read_b128 v[150:153], v229 offset:20480
	s_waitcnt lgkmcnt(1)
	v_mfma_f32_32x32x16_bf16 v[48:63], v[142:145], v[146:149], v[48:63]
	s_waitcnt lgkmcnt(0)
	v_mfma_f32_32x32x16_bf16 v[32:47], v[142:145], v[150:153], v[32:47]
	ds_read_b128 v[142:145], v131 offset:4096
	s_waitcnt lgkmcnt(0)
	v_mfma_f32_32x32x16_bf16 v[16:31], v[142:145], v[146:149], v[16:31]
	v_mfma_f32_32x32x16_bf16 v[0:15], v[142:145], v[150:153], v[0:15]
	s_waitcnt vmcnt(0)
	ds_write_b128 v134, v[196:199] offset:32768
	ds_write_b128 v134, v[212:215] offset:49152
	ds_write_b128 v134, v[200:203] offset:36864
	ds_write_b128 v134, v[216:219] offset:53248
	ds_write_b128 v134, v[204:207] offset:40960
	ds_write_b128 v134, v[220:223] offset:57344
	ds_write_b128 v134, v[208:211] offset:45056
	ds_write_b128 v134, v[224:227] offset:61440
	s_waitcnt lgkmcnt(0)
	s_barrier
	ds_read_b128 v[142:145], v128 offset:32768
	ds_read_b128 v[146:149], v132 offset:49152
	ds_read_b128 v[150:153], v132 offset:53248
	s_waitcnt lgkmcnt(1)
	v_mfma_f32_32x32x16_bf16 v[48:63], v[142:145], v[146:149], v[48:63]
	s_waitcnt lgkmcnt(0)
	v_mfma_f32_32x32x16_bf16 v[32:47], v[142:145], v[150:153], v[32:47]
	ds_read_b128 v[142:145], v128 offset:36864
	s_waitcnt lgkmcnt(0)
	v_mfma_f32_32x32x16_bf16 v[16:31], v[142:145], v[146:149], v[16:31]
	ds_read_b128 v[146:149], v133 offset:49152
	v_mfma_f32_32x32x16_bf16 v[0:15], v[142:145], v[150:153], v[0:15]
	ds_read_b128 v[142:145], v129 offset:32768
	ds_read_b128 v[150:153], v133 offset:53248
	s_waitcnt lgkmcnt(1)
	v_mfma_f32_32x32x16_bf16 v[48:63], v[142:145], v[146:149], v[48:63]
	s_waitcnt lgkmcnt(0)
	v_mfma_f32_32x32x16_bf16 v[32:47], v[142:145], v[150:153], v[32:47]
	ds_read_b128 v[142:145], v129 offset:36864
	s_waitcnt lgkmcnt(0)
	v_mfma_f32_32x32x16_bf16 v[16:31], v[142:145], v[146:149], v[16:31]
	ds_read_b128 v[146:149], v228 offset:49152
	v_mfma_f32_32x32x16_bf16 v[0:15], v[142:145], v[150:153], v[0:15]
	ds_read_b128 v[142:145], v130 offset:32768
	ds_read_b128 v[150:153], v228 offset:53248
	s_waitcnt lgkmcnt(1)
	v_mfma_f32_32x32x16_bf16 v[48:63], v[142:145], v[146:149], v[48:63]
	s_waitcnt lgkmcnt(0)
	v_mfma_f32_32x32x16_bf16 v[32:47], v[142:145], v[150:153], v[32:47]
	ds_read_b128 v[142:145], v130 offset:36864
	s_waitcnt lgkmcnt(0)
	v_mfma_f32_32x32x16_bf16 v[16:31], v[142:145], v[146:149], v[16:31]
	ds_read_b128 v[146:149], v229 offset:49152
	v_mfma_f32_32x32x16_bf16 v[0:15], v[142:145], v[150:153], v[0:15]
	ds_read_b128 v[142:145], v131 offset:32768
	ds_read_b128 v[150:153], v229 offset:53248
	s_waitcnt lgkmcnt(1)
	v_mfma_f32_32x32x16_bf16 v[48:63], v[142:145], v[146:149], v[48:63]
	s_waitcnt lgkmcnt(0)
	v_mfma_f32_32x32x16_bf16 v[32:47], v[142:145], v[150:153], v[32:47]
	ds_read_b128 v[142:145], v131 offset:36864
	s_waitcnt lgkmcnt(0)
	v_mfma_f32_32x32x16_bf16 v[16:31], v[142:145], v[146:149], v[16:31]
	v_mfma_f32_32x32x16_bf16 v[0:15], v[142:145], v[150:153], v[0:15]
	s_barrier
	s_branch .Lsha_s5y_j
.Lsha_s5y_h1:
	global_load_dwordx4 v[80:83], v231, s[22:23]
	global_load_dwordx4 v[84:87], v231, s[54:55]
	global_load_dwordx4 v[88:91], v231, s[72:73]
	global_load_dwordx4 v[92:95], v231, s[74:75]
	global_load_dwordx4 v[112:115], v231, s[22:23] offset:128
	global_load_dwordx4 v[116:119], v231, s[54:55] offset:128
	global_load_dwordx4 v[120:123], v231, s[72:73] offset:128
	global_load_dwordx4 v[124:127], v231, s[74:75] offset:128
	global_load_dwordx4 v[176:179], v231, s[22:23] offset:256
	global_load_dwordx4 v[180:183], v231, s[54:55] offset:256
	global_load_dwordx4 v[184:187], v231, s[72:73] offset:256
	global_load_dwordx4 v[188:191], v231, s[74:75] offset:256
	global_load_dwordx4 v[212:215], v231, s[22:23] offset:384
	global_load_dwordx4 v[216:219], v231, s[54:55] offset:384
	global_load_dwordx4 v[220:223], v231, s[72:73] offset:384
	global_load_dwordx4 v[224:227], v231, s[74:75] offset:384
	v_add_u32_e32 v128, v135, v137
	v_add_u32_e32 v132, v136, v137
	v_add_u32_e32 v129, v135, v138
	v_add_u32_e32 v133, v136, v138
	v_add_u32_e32 v130, v135, v139
	v_add_u32_e32 v228, v136, v139
	v_add_u32_e32 v131, v135, v140
	v_add_u32_e32 v128, 0xffff0000, v128
	v_add_u32_e32 v129, 0xffff0000, v129
	v_add_u32_e32 v130, 0xffff0000, v130
	v_add_u32_e32 v131, 0xffff0000, v131
	v_add_u32_e32 v229, v136, v140
	v_mov_b32_e32 v0, 0
	v_mov_b32_e32 v1, v0
	v_mov_b32_e32 v2, v0
	v_mov_b32_e32 v3, v0
	v_mov_b32_e32 v4, v0
	v_mov_b32_e32 v5, v0
	v_mov_b32_e32 v6, v0
	v_mov_b32_e32 v7, v0
	v_mov_b32_e32 v8, v0
	v_mov_b32_e32 v9, v0
	v_mov_b32_e32 v10, v0
	v_mov_b32_e32 v11, v0
	v_mov_b32_e32 v12, v0
	v_mov_b32_e32 v13, v0
	v_mov_b32_e32 v14, v0
	v_mov_b32_e32 v15, v0
	v_mov_b32_e32 v16, v0
	v_mov_b32_e32 v17, v0
	v_mov_b32_e32 v18, v0
	v_mov_b32_e32 v19, v0
	v_mov_b32_e32 v20, v0
	v_mov_b32_e32 v21, v0
	v_mov_b32_e32 v22, v0
	v_mov_b32_e32 v23, v0
	v_mov_b32_e32 v24, v0
	v_mov_b32_e32 v25, v0
	v_mov_b32_e32 v26, v0
	v_mov_b32_e32 v27, v0
	v_mov_b32_e32 v28, v0
	v_mov_b32_e32 v29, v0
	v_mov_b32_e32 v30, v0
	v_mov_b32_e32 v31, v0
	v_mov_b32_e32 v32, v0
	v_mov_b32_e32 v33, v0
	v_mov_b32_e32 v34, v0
	v_mov_b32_e32 v35, v0
	v_mov_b32_e32 v36, v0
	v_mov_b32_e32 v37, v0
	v_mov_b32_e32 v38, v0
	v_mov_b32_e32 v39, v0
	v_mov_b32_e32 v40, v0
	v_mov_b32_e32 v41, v0
	v_mov_b32_e32 v42, v0
	v_mov_b32_e32 v43, v0
	v_mov_b32_e32 v44, v0
	v_mov_b32_e32 v45, v0
	v_mov_b32_e32 v46, v0
	v_mov_b32_e32 v47, v0
	v_mov_b32_e32 v48, v0
	v_mov_b32_e32 v49, v0
	v_mov_b32_e32 v50, v0
	v_mov_b32_e32 v51, v0
	v_mov_b32_e32 v52, v0
	v_mov_b32_e32 v53, v0
	v_mov_b32_e32 v54, v0
	v_mov_b32_e32 v55, v0
	v_mov_b32_e32 v56, v0
	v_mov_b32_e32 v57, v0
	v_mov_b32_e32 v58, v0
	v_mov_b32_e32 v59, v0
	v_mov_b32_e32 v60, v0
	v_mov_b32_e32 v61, v0
	v_mov_b32_e32 v62, v0
	v_mov_b32_e32 v63, v0
	s_waitcnt vmcnt(12)
	ds_write_b128 v134, v[80:83] offset:16384
	ds_write_b128 v134, v[84:87] offset:20480
	ds_write_b128 v134, v[88:91] offset:24576
	ds_write_b128 v134, v[92:95] offset:28672
	s_waitcnt lgkmcnt(0)
	s_barrier
	global_load_dwordx4 v[80:83], v231, s[22:23] offset:512
	global_load_dwordx4 v[84:87], v231, s[54:55] offset:512
	global_load_dwordx4 v[88:91], v231, s[72:73] offset:512
	global_load_dwordx4 v[92:95], v231, s[74:75] offset:512
	ds_read_b128 v[142:145], v128
	ds_read_b128 v[146:149], v132 offset:16384
	ds_read_b128 v[150:153], v132 offset:20480
	s_waitcnt lgkmcnt(1)
	v_mfma_f32_32x32x16_bf16 v[48:63], v[142:145], v[146:149], v[48:63]
	s_waitcnt lgkmcnt(0)
	v_mfma_f32_32x32x16_bf16 v[32:47], v[142:145], v[150:153], v[32:47]
	ds_read_b128 v[142:145], v128 offset:4096
	s_waitcnt lgkmcnt(0)
	v_mfma_f32_32x32x16_bf16 v[16:31], v[142:145], v[146:149], v[16:31]
	ds_read_b128 v[146:149], v133 offset:16384
	v_mfma_f32_32x32x16_bf16 v[0:15], v[142:145], v[150:153], v[0:15]
	ds_read_b128 v[142:145], v129
	ds_read_b128 v[150:153], v133 offset:20480
	s_waitcnt lgkmcnt(1)
	v_mfma_f32_32x32x16_bf16 v[48:63], v[142:145], v[146:149], v[48:63]
	s_waitcnt lgkmcnt(0)
	v_mfma_f32_32x32x16_bf16 v[32:47], v[142:145], v[150:153], v[32:47]
	ds_read_b128 v[142:145], v129 offset:4096
	s_waitcnt lgkmcnt(0)
	v_mfma_f32_32x32x16_bf16 v[16:31], v[142:145], v[146:149], v[16:31]
	ds_read_b128 v[146:149], v228 offset:16384
	v_mfma_f32_32x32x16_bf16 v[0:15], v[142:145], v[150:153], v[0:15]
	ds_read_b128 v[142:145], v130
	ds_read_b128 v[150:153], v228 offset:20480
	s_waitcnt lgkmcnt(1)
	v_mfma_f32_32x32x16_bf16 v[48:63], v[142:145], v[146:149], v[48:63]
	s_waitcnt lgkmcnt(0)
	v_mfma_f32_32x32x16_bf16 v[32:47], v[142:145], v[150:153], v[32:47]
	ds_read_b128 v[142:145], v130 offset:4096
	s_waitcnt lgkmcnt(0)
	v_mfma_f32_32x32x16_bf16 v[16:31], v[142:145], v[146:149], v[16:31]
	ds_read_b128 v[146:149], v229 offset:16384
	v_mfma_f32_32x32x16_bf16 v[0:15], v[142:145], v[150:153], v[0:15]
	ds_read_b128 v[142:145], v131
	ds_read_b128 v[150:153], v229 offset:20480
	s_waitcnt lgkmcnt(1)
	v_mfma_f32_32x32x16_bf16 v[48:63], v[142:145], v[146:149], v[48:63]
	s_waitcnt lgkmcnt(0)
	v_mfma_f32_32x32x16_bf16 v[32:47], v[142:145], v[150:153], v[32:47]
	ds_read_b128 v[142:145], v131 offset:4096
	s_waitcnt lgkmcnt(0)
	v_mfma_f32_32x32x16_bf16 v[16:31], v[142:145], v[146:149], v[16:31]
	v_mfma_f32_32x32x16_bf16 v[0:15], v[142:145], v[150:153], v[0:15]
	s_waitcnt vmcnt(12)
	ds_write_b128 v134, v[112:115] offset:49152
	ds_write_b128 v134, v[116:119] offset:53248
	ds_write_b128 v134, v[120:123] offset:57344
	ds_write_b128 v134, v[124:127] offset:61440
	s_waitcnt lgkmcnt(0)
	s_barrier
	global_load_dwordx4 v[112:115], v231, s[22:23] offset:640
	global_load_dwordx4 v[116:119], v231, s[54:55] offset:640
	global_load_dwordx4 v[120:123], v231, s[72:73] offset:640
	global_load_dwordx4 v[124:127], v231, s[74:75] offset:640
	ds_read_b128 v[142:145], v128 offset:32768
	ds_read_b128 v[146:149], v132 offset:49152
	ds_read_b128 v[150:153], v132 offset:53248
	s_waitcnt lgkmcnt(1)
	v_mfma_f32_32x32x16_bf16 v[48:63], v[142:145], v[146:149], v[48:63]
	s_waitcnt lgkmcnt(0)
	v_mfma_f32_32x32x16_bf16 v[32:47], v[142:145], v[150:153], v[32:47]
	ds_read_b128 v[142:145], v128 offset:36864
	s_waitcnt lgkmcnt(0)
	v_mfma_f32_32x32x16_bf16 v[16:31], v[142:145], v[146:149], v[16:31]
	ds_read_b128 v[146:149], v133 offset:49152
	v_mfma_f32_32x32x16_bf16 v[0:15], v[142:145], v[150:153], v[0:15]
	ds_read_b128 v[142:145], v129 offset:32768
	ds_read_b128 v[150:153], v133 offset:53248
	s_waitcnt lgkmcnt(1)
	v_mfma_f32_32x32x16_bf16 v[48:63], v[142:145], v[146:149], v[48:63]
	s_waitcnt lgkmcnt(0)
	v_mfma_f32_32x32x16_bf16 v[32:47], v[142:145], v[150:153], v[32:47]
	ds_read_b128 v[142:145], v129 offset:36864
	s_waitcnt lgkmcnt(0)
	v_mfma_f32_32x32x16_bf16 v[16:31], v[142:145], v[146:149], v[16:31]
	ds_read_b128 v[146:149], v228 offset:49152
	v_mfma_f32_32x32x16_bf16 v[0:15], v[142:145], v[150:153], v[0:15]
	ds_read_b128 v[142:145], v130 offset:32768
	ds_read_b128 v[150:153], v228 offset:53248
	s_waitcnt lgkmcnt(1)
	v_mfma_f32_32x32x16_bf16 v[48:63], v[142:145], v[146:149], v[48:63]
	s_waitcnt lgkmcnt(0)
	v_mfma_f32_32x32x16_bf16 v[32:47], v[142:145], v[150:153], v[32:47]
	ds_read_b128 v[142:145], v130 offset:36864
	s_waitcnt lgkmcnt(0)
	v_mfma_f32_32x32x16_bf16 v[16:31], v[142:145], v[146:149], v[16:31]
	ds_read_b128 v[146:149], v229 offset:49152
	v_mfma_f32_32x32x16_bf16 v[0:15], v[142:145], v[150:153], v[0:15]
	ds_read_b128 v[142:145], v131 offset:32768
	ds_read_b128 v[150:153], v229 offset:53248
	s_waitcnt lgkmcnt(1)
	v_mfma_f32_32x32x16_bf16 v[48:63], v[142:145], v[146:149], v[48:63]
	s_waitcnt lgkmcnt(0)
	v_mfma_f32_32x32x16_bf16 v[32:47], v[142:145], v[150:153], v[32:47]
	ds_read_b128 v[142:145], v131 offset:36864
	s_waitcnt lgkmcnt(0)
	v_mfma_f32_32x32x16_bf16 v[16:31], v[142:145], v[146:149], v[16:31]
	v_mfma_f32_32x32x16_bf16 v[0:15], v[142:145], v[150:153], v[0:15]
	s_waitcnt vmcnt(12)
	ds_write_b128 v134, v[176:179] offset:16384
	ds_write_b128 v134, v[180:183] offset:20480
	ds_write_b128 v134, v[184:187] offset:24576
	ds_write_b128 v134, v[188:191] offset:28672
	s_waitcnt lgkmcnt(0)
	s_barrier
	global_load_dwordx4 v[176:179], v231, s[22:23] offset:768
	global_load_dwordx4 v[180:183], v231, s[54:55] offset:768
	global_load_dwordx4 v[184:187], v231, s[72:73] offset:768
	global_load_dwordx4 v[188:191], v231, s[74:75] offset:768
	ds_read_b128 v[142:145], v128
	ds_read_b128 v[146:149], v132 offset:16384
	ds_read_b128 v[150:153], v132 offset:20480
	s_waitcnt lgkmcnt(1)
	v_mfma_f32_32x32x16_bf16 v[48:63], v[142:145], v[146:149], v[48:63]
	s_waitcnt lgkmcnt(0)
	v_mfma_f32_32x32x16_bf16 v[32:47], v[142:145], v[150:153], v[32:47]
	ds_read_b128 v[142:145], v128 offset:4096
	s_waitcnt lgkmcnt(0)
	v_mfma_f32_32x32x16_bf16 v[16:31], v[142:145], v[146:149], v[16:31]
	ds_read_b128 v[146:149], v133 offset:16384
	v_mfma_f32_32x32x16_bf16 v[0:15], v[142:145], v[150:153], v[0:15]
	ds_read_b128 v[142:145], v129
	ds_read_b128 v[150:153], v133 offset:20480
	s_waitcnt lgkmcnt(1)
	v_mfma_f32_32x32x16_bf16 v[48:63], v[142:145], v[146:149], v[48:63]
	s_waitcnt lgkmcnt(0)
	v_mfma_f32_32x32x16_bf16 v[32:47], v[142:145], v[150:153], v[32:47]
	ds_read_b128 v[142:145], v129 offset:4096
	s_waitcnt lgkmcnt(0)
	v_mfma_f32_32x32x16_bf16 v[16:31], v[142:145], v[146:149], v[16:31]
	ds_read_b128 v[146:149], v228 offset:16384
	v_mfma_f32_32x32x16_bf16 v[0:15], v[142:145], v[150:153], v[0:15]
	ds_read_b128 v[142:145], v130
	ds_read_b128 v[150:153], v228 offset:20480
	s_waitcnt lgkmcnt(1)
	v_mfma_f32_32x32x16_bf16 v[48:63], v[142:145], v[146:149], v[48:63]
	s_waitcnt lgkmcnt(0)
	v_mfma_f32_32x32x16_bf16 v[32:47], v[142:145], v[150:153], v[32:47]
	ds_read_b128 v[142:145], v130 offset:4096
	s_waitcnt lgkmcnt(0)
	v_mfma_f32_32x32x16_bf16 v[16:31], v[142:145], v[146:149], v[16:31]
	ds_read_b128 v[146:149], v229 offset:16384
	v_mfma_f32_32x32x16_bf16 v[0:15], v[142:145], v[150:153], v[0:15]
	ds_read_b128 v[142:145], v131
	ds_read_b128 v[150:153], v229 offset:20480
	s_waitcnt lgkmcnt(1)
	v_mfma_f32_32x32x16_bf16 v[48:63], v[142:145], v[146:149], v[48:63]
	s_waitcnt lgkmcnt(0)
	v_mfma_f32_32x32x16_bf16 v[32:47], v[142:145], v[150:153], v[32:47]
	ds_read_b128 v[142:145], v131 offset:4096
	s_waitcnt lgkmcnt(0)
	v_mfma_f32_32x32x16_bf16 v[16:31], v[142:145], v[146:149], v[16:31]
	v_mfma_f32_32x32x16_bf16 v[0:15], v[142:145], v[150:153], v[0:15]
	s_waitcnt vmcnt(12)
	ds_write_b128 v134, v[212:215] offset:49152
	ds_write_b128 v134, v[216:219] offset:53248
	ds_write_b128 v134, v[220:223] offset:57344
	ds_write_b128 v134, v[224:227] offset:61440
	s_waitcnt lgkmcnt(0)
	s_barrier
	global_load_dwordx4 v[212:215], v231, s[22:23] offset:896
	global_load_dwordx4 v[216:219], v231, s[54:55] offset:896
	global_load_dwordx4 v[220:223], v231, s[72:73] offset:896
	global_load_dwordx4 v[224:227], v231, s[74:75] offset:896
	ds_read_b128 v[142:145], v128 offset:32768
	ds_read_b128 v[146:149], v132 offset:49152
	ds_read_b128 v[150:153], v132 offset:53248
	s_waitcnt lgkmcnt(1)
	v_mfma_f32_32x32x16_bf16 v[48:63], v[142:145], v[146:149], v[48:63]
	s_waitcnt lgkmcnt(0)
	v_mfma_f32_32x32x16_bf16 v[32:47], v[142:145], v[150:153], v[32:47]
	ds_read_b128 v[142:145], v128 offset:36864
	s_waitcnt lgkmcnt(0)
	v_mfma_f32_32x32x16_bf16 v[16:31], v[142:145], v[146:149], v[16:31]
	ds_read_b128 v[146:149], v133 offset:49152
	v_mfma_f32_32x32x16_bf16 v[0:15], v[142:145], v[150:153], v[0:15]
	ds_read_b128 v[142:145], v129 offset:32768
	ds_read_b128 v[150:153], v133 offset:53248
	s_waitcnt lgkmcnt(1)
	v_mfma_f32_32x32x16_bf16 v[48:63], v[142:145], v[146:149], v[48:63]
	s_waitcnt lgkmcnt(0)
	v_mfma_f32_32x32x16_bf16 v[32:47], v[142:145], v[150:153], v[32:47]
	ds_read_b128 v[142:145], v129 offset:36864
	s_waitcnt lgkmcnt(0)
	v_mfma_f32_32x32x16_bf16 v[16:31], v[142:145], v[146:149], v[16:31]
	ds_read_b128 v[146:149], v228 offset:49152
	v_mfma_f32_32x32x16_bf16 v[0:15], v[142:145], v[150:153], v[0:15]
	ds_read_b128 v[142:145], v130 offset:32768
	ds_read_b128 v[150:153], v228 offset:53248
	s_waitcnt lgkmcnt(1)
	v_mfma_f32_32x32x16_bf16 v[48:63], v[142:145], v[146:149], v[48:63]
	s_waitcnt lgkmcnt(0)
	v_mfma_f32_32x32x16_bf16 v[32:47], v[142:145], v[150:153], v[32:47]
	ds_read_b128 v[142:145], v130 offset:36864
	s_waitcnt lgkmcnt(0)
	v_mfma_f32_32x32x16_bf16 v[16:31], v[142:145], v[146:149], v[16:31]
	ds_read_b128 v[146:149], v229 offset:49152
	v_mfma_f32_32x32x16_bf16 v[0:15], v[142:145], v[150:153], v[0:15]
	ds_read_b128 v[142:145], v131 offset:32768
	ds_read_b128 v[150:153], v229 offset:53248
	s_waitcnt lgkmcnt(1)
	v_mfma_f32_32x32x16_bf16 v[48:63], v[142:145], v[146:149], v[48:63]
	s_waitcnt lgkmcnt(0)
	v_mfma_f32_32x32x16_bf16 v[32:47], v[142:145], v[150:153], v[32:47]
	ds_read_b128 v[142:145], v131 offset:36864
	s_waitcnt lgkmcnt(0)
	v_mfma_f32_32x32x16_bf16 v[16:31], v[142:145], v[146:149], v[16:31]
	v_mfma_f32_32x32x16_bf16 v[0:15], v[142:145], v[150:153], v[0:15]
	s_waitcnt vmcnt(12)
	ds_write_b128 v134, v[80:83] offset:16384
	ds_write_b128 v134, v[84:87] offset:20480
	ds_write_b128 v134, v[88:91] offset:24576
	ds_write_b128 v134, v[92:95] offset:28672
	s_waitcnt lgkmcnt(0)
	s_barrier
	global_load_dwordx4 v[80:83], v231, s[22:23] offset:1024
	global_load_dwordx4 v[84:87], v231, s[54:55] offset:1024
	global_load_dwordx4 v[88:91], v231, s[72:73] offset:1024
	global_load_dwordx4 v[92:95], v231, s[74:75] offset:1024
	ds_read_b128 v[142:145], v128
	ds_read_b128 v[146:149], v132 offset:16384
	ds_read_b128 v[150:153], v132 offset:20480
	s_waitcnt lgkmcnt(1)
	v_mfma_f32_32x32x16_bf16 v[48:63], v[142:145], v[146:149], v[48:63]
	s_waitcnt lgkmcnt(0)
	v_mfma_f32_32x32x16_bf16 v[32:47], v[142:145], v[150:153], v[32:47]
	ds_read_b128 v[142:145], v128 offset:4096
	s_waitcnt lgkmcnt(0)
	v_mfma_f32_32x32x16_bf16 v[16:31], v[142:145], v[146:149], v[16:31]
	ds_read_b128 v[146:149], v133 offset:16384
	v_mfma_f32_32x32x16_bf16 v[0:15], v[142:145], v[150:153], v[0:15]
	ds_read_b128 v[142:145], v129
	ds_read_b128 v[150:153], v133 offset:20480
	s_waitcnt lgkmcnt(1)
	v_mfma_f32_32x32x16_bf16 v[48:63], v[142:145], v[146:149], v[48:63]
	s_waitcnt lgkmcnt(0)
	v_mfma_f32_32x32x16_bf16 v[32:47], v[142:145], v[150:153], v[32:47]
	ds_read_b128 v[142:145], v129 offset:4096
	s_waitcnt lgkmcnt(0)
	v_mfma_f32_32x32x16_bf16 v[16:31], v[142:145], v[146:149], v[16:31]
	ds_read_b128 v[146:149], v228 offset:16384
	v_mfma_f32_32x32x16_bf16 v[0:15], v[142:145], v[150:153], v[0:15]
	ds_read_b128 v[142:145], v130
	ds_read_b128 v[150:153], v228 offset:20480
	s_waitcnt lgkmcnt(1)
	v_mfma_f32_32x32x16_bf16 v[48:63], v[142:145], v[146:149], v[48:63]
	s_waitcnt lgkmcnt(0)
	v_mfma_f32_32x32x16_bf16 v[32:47], v[142:145], v[150:153], v[32:47]
	ds_read_b128 v[142:145], v130 offset:4096
	s_waitcnt lgkmcnt(0)
	v_mfma_f32_32x32x16_bf16 v[16:31], v[142:145], v[146:149], v[16:31]
	ds_read_b128 v[146:149], v229 offset:16384
	v_mfma_f32_32x32x16_bf16 v[0:15], v[142:145], v[150:153], v[0:15]
	ds_read_b128 v[142:145], v131
	ds_read_b128 v[150:153], v229 offset:20480
	s_waitcnt lgkmcnt(1)
	v_mfma_f32_32x32x16_bf16 v[48:63], v[142:145], v[146:149], v[48:63]
	s_waitcnt lgkmcnt(0)
	v_mfma_f32_32x32x16_bf16 v[32:47], v[142:145], v[150:153], v[32:47]
	ds_read_b128 v[142:145], v131 offset:4096
	s_waitcnt lgkmcnt(0)
	v_mfma_f32_32x32x16_bf16 v[16:31], v[142:145], v[146:149], v[16:31]
	v_mfma_f32_32x32x16_bf16 v[0:15], v[142:145], v[150:153], v[0:15]
	s_waitcnt vmcnt(12)
	ds_write_b128 v134, v[112:115] offset:49152
	ds_write_b128 v134, v[116:119] offset:53248
	ds_write_b128 v134, v[120:123] offset:57344
	ds_write_b128 v134, v[124:127] offset:61440
	s_waitcnt lgkmcnt(0)
	s_barrier
	global_load_dwordx4 v[112:115], v231, s[22:23] offset:1152
	global_load_dwordx4 v[116:119], v231, s[54:55] offset:1152
	global_load_dwordx4 v[120:123], v231, s[72:73] offset:1152
	global_load_dwordx4 v[124:127], v231, s[74:75] offset:1152
	ds_read_b128 v[142:145], v128 offset:32768
	ds_read_b128 v[146:149], v132 offset:49152
	ds_read_b128 v[150:153], v132 offset:53248
	s_waitcnt lgkmcnt(1)
	v_mfma_f32_32x32x16_bf16 v[48:63], v[142:145], v[146:149], v[48:63]
	s_waitcnt lgkmcnt(0)
	v_mfma_f32_32x32x16_bf16 v[32:47], v[142:145], v[150:153], v[32:47]
	ds_read_b128 v[142:145], v128 offset:36864
	s_waitcnt lgkmcnt(0)
	v_mfma_f32_32x32x16_bf16 v[16:31], v[142:145], v[146:149], v[16:31]
	ds_read_b128 v[146:149], v133 offset:49152
	v_mfma_f32_32x32x16_bf16 v[0:15], v[142:145], v[150:153], v[0:15]
	ds_read_b128 v[142:145], v129 offset:32768
	ds_read_b128 v[150:153], v133 offset:53248
	s_waitcnt lgkmcnt(1)
	v_mfma_f32_32x32x16_bf16 v[48:63], v[142:145], v[146:149], v[48:63]
	s_waitcnt lgkmcnt(0)
	v_mfma_f32_32x32x16_bf16 v[32:47], v[142:145], v[150:153], v[32:47]
	ds_read_b128 v[142:145], v129 offset:36864
	s_waitcnt lgkmcnt(0)
	v_mfma_f32_32x32x16_bf16 v[16:31], v[142:145], v[146:149], v[16:31]
	ds_read_b128 v[146:149], v228 offset:49152
	v_mfma_f32_32x32x16_bf16 v[0:15], v[142:145], v[150:153], v[0:15]
	ds_read_b128 v[142:145], v130 offset:32768
	ds_read_b128 v[150:153], v228 offset:53248
	s_waitcnt lgkmcnt(1)
	v_mfma_f32_32x32x16_bf16 v[48:63], v[142:145], v[146:149], v[48:63]
	s_waitcnt lgkmcnt(0)
	v_mfma_f32_32x32x16_bf16 v[32:47], v[142:145], v[150:153], v[32:47]
	ds_read_b128 v[142:145], v130 offset:36864
	s_waitcnt lgkmcnt(0)
	v_mfma_f32_32x32x16_bf16 v[16:31], v[142:145], v[146:149], v[16:31]
	ds_read_b128 v[146:149], v229 offset:49152
	v_mfma_f32_32x32x16_bf16 v[0:15], v[142:145], v[150:153], v[0:15]
	ds_read_b128 v[142:145], v131 offset:32768
	ds_read_b128 v[150:153], v229 offset:53248
	s_waitcnt lgkmcnt(1)
	v_mfma_f32_32x32x16_bf16 v[48:63], v[142:145], v[146:149], v[48:63]
	s_waitcnt lgkmcnt(0)
	v_mfma_f32_32x32x16_bf16 v[32:47], v[142:145], v[150:153], v[32:47]
	ds_read_b128 v[142:145], v131 offset:36864
	s_waitcnt lgkmcnt(0)
	v_mfma_f32_32x32x16_bf16 v[16:31], v[142:145], v[146:149], v[16:31]
	v_mfma_f32_32x32x16_bf16 v[0:15], v[142:145], v[150:153], v[0:15]
	s_waitcnt vmcnt(12)
	ds_write_b128 v134, v[176:179] offset:16384
	ds_write_b128 v134, v[180:183] offset:20480
	ds_write_b128 v134, v[184:187] offset:24576
	ds_write_b128 v134, v[188:191] offset:28672
	s_waitcnt lgkmcnt(0)
	s_barrier
	global_load_dwordx4 v[176:179], v231, s[22:23] offset:1280
	global_load_dwordx4 v[180:183], v231, s[54:55] offset:1280
	global_load_dwordx4 v[184:187], v231, s[72:73] offset:1280
	global_load_dwordx4 v[188:191], v231, s[74:75] offset:1280
	ds_read_b128 v[142:145], v128
	ds_read_b128 v[146:149], v132 offset:16384
	ds_read_b128 v[150:153], v132 offset:20480
	s_waitcnt lgkmcnt(1)
	v_mfma_f32_32x32x16_bf16 v[48:63], v[142:145], v[146:149], v[48:63]
	s_waitcnt lgkmcnt(0)
	v_mfma_f32_32x32x16_bf16 v[32:47], v[142:145], v[150:153], v[32:47]
	ds_read_b128 v[142:145], v128 offset:4096
	s_waitcnt lgkmcnt(0)
	v_mfma_f32_32x32x16_bf16 v[16:31], v[142:145], v[146:149], v[16:31]
	ds_read_b128 v[146:149], v133 offset:16384
	v_mfma_f32_32x32x16_bf16 v[0:15], v[142:145], v[150:153], v[0:15]
	ds_read_b128 v[142:145], v129
	ds_read_b128 v[150:153], v133 offset:20480
	s_waitcnt lgkmcnt(1)
	v_mfma_f32_32x32x16_bf16 v[48:63], v[142:145], v[146:149], v[48:63]
	s_waitcnt lgkmcnt(0)
	v_mfma_f32_32x32x16_bf16 v[32:47], v[142:145], v[150:153], v[32:47]
	ds_read_b128 v[142:145], v129 offset:4096
	s_waitcnt lgkmcnt(0)
	v_mfma_f32_32x32x16_bf16 v[16:31], v[142:145], v[146:149], v[16:31]
	ds_read_b128 v[146:149], v228 offset:16384
	v_mfma_f32_32x32x16_bf16 v[0:15], v[142:145], v[150:153], v[0:15]
	ds_read_b128 v[142:145], v130
	ds_read_b128 v[150:153], v228 offset:20480
	s_waitcnt lgkmcnt(1)
	v_mfma_f32_32x32x16_bf16 v[48:63], v[142:145], v[146:149], v[48:63]
	s_waitcnt lgkmcnt(0)
	v_mfma_f32_32x32x16_bf16 v[32:47], v[142:145], v[150:153], v[32:47]
	ds_read_b128 v[142:145], v130 offset:4096
	s_waitcnt lgkmcnt(0)
	v_mfma_f32_32x32x16_bf16 v[16:31], v[142:145], v[146:149], v[16:31]
	ds_read_b128 v[146:149], v229 offset:16384
	v_mfma_f32_32x32x16_bf16 v[0:15], v[142:145], v[150:153], v[0:15]
	ds_read_b128 v[142:145], v131
	ds_read_b128 v[150:153], v229 offset:20480
	s_waitcnt lgkmcnt(1)
	v_mfma_f32_32x32x16_bf16 v[48:63], v[142:145], v[146:149], v[48:63]
	s_waitcnt lgkmcnt(0)
	v_mfma_f32_32x32x16_bf16 v[32:47], v[142:145], v[150:153], v[32:47]
	ds_read_b128 v[142:145], v131 offset:4096
	s_waitcnt lgkmcnt(0)
	v_mfma_f32_32x32x16_bf16 v[16:31], v[142:145], v[146:149], v[16:31]
	v_mfma_f32_32x32x16_bf16 v[0:15], v[142:145], v[150:153], v[0:15]
	s_waitcnt vmcnt(12)
	ds_write_b128 v134, v[212:215] offset:49152
	ds_write_b128 v134, v[216:219] offset:53248
	ds_write_b128 v134, v[220:223] offset:57344
	ds_write_b128 v134, v[224:227] offset:61440
	s_waitcnt lgkmcnt(0)
	s_barrier
	global_load_dwordx4 v[212:215], v231, s[22:23] offset:1408
	global_load_dwordx4 v[216:219], v231, s[54:55] offset:1408
	global_load_dwordx4 v[220:223], v231, s[72:73] offset:1408
	global_load_dwordx4 v[224:227], v231, s[74:75] offset:1408
	ds_read_b128 v[142:145], v128 offset:32768
	ds_read_b128 v[146:149], v132 offset:49152
	ds_read_b128 v[150:153], v132 offset:53248
	s_waitcnt lgkmcnt(1)
	v_mfma_f32_32x32x16_bf16 v[48:63], v[142:145], v[146:149], v[48:63]
	s_waitcnt lgkmcnt(0)
	v_mfma_f32_32x32x16_bf16 v[32:47], v[142:145], v[150:153], v[32:47]
	ds_read_b128 v[142:145], v128 offset:36864
	s_waitcnt lgkmcnt(0)
	v_mfma_f32_32x32x16_bf16 v[16:31], v[142:145], v[146:149], v[16:31]
	ds_read_b128 v[146:149], v133 offset:49152
	v_mfma_f32_32x32x16_bf16 v[0:15], v[142:145], v[150:153], v[0:15]
	ds_read_b128 v[142:145], v129 offset:32768
	ds_read_b128 v[150:153], v133 offset:53248
	s_waitcnt lgkmcnt(1)
	v_mfma_f32_32x32x16_bf16 v[48:63], v[142:145], v[146:149], v[48:63]
	s_waitcnt lgkmcnt(0)
	v_mfma_f32_32x32x16_bf16 v[32:47], v[142:145], v[150:153], v[32:47]
	ds_read_b128 v[142:145], v129 offset:36864
	s_waitcnt lgkmcnt(0)
	v_mfma_f32_32x32x16_bf16 v[16:31], v[142:145], v[146:149], v[16:31]
	ds_read_b128 v[146:149], v228 offset:49152
	v_mfma_f32_32x32x16_bf16 v[0:15], v[142:145], v[150:153], v[0:15]
	ds_read_b128 v[142:145], v130 offset:32768
	ds_read_b128 v[150:153], v228 offset:53248
	s_waitcnt lgkmcnt(1)
	v_mfma_f32_32x32x16_bf16 v[48:63], v[142:145], v[146:149], v[48:63]
	s_waitcnt lgkmcnt(0)
	v_mfma_f32_32x32x16_bf16 v[32:47], v[142:145], v[150:153], v[32:47]
	ds_read_b128 v[142:145], v130 offset:36864
	s_waitcnt lgkmcnt(0)
	v_mfma_f32_32x32x16_bf16 v[16:31], v[142:145], v[146:149], v[16:31]
	ds_read_b128 v[146:149], v229 offset:49152
	v_mfma_f32_32x32x16_bf16 v[0:15], v[142:145], v[150:153], v[0:15]
	ds_read_b128 v[142:145], v131 offset:32768
	ds_read_b128 v[150:153], v229 offset:53248
	s_waitcnt lgkmcnt(1)
	v_mfma_f32_32x32x16_bf16 v[48:63], v[142:145], v[146:149], v[48:63]
	s_waitcnt lgkmcnt(0)
	v_mfma_f32_32x32x16_bf16 v[32:47], v[142:145], v[150:153], v[32:47]
	ds_read_b128 v[142:145], v131 offset:36864
	s_waitcnt lgkmcnt(0)
	v_mfma_f32_32x32x16_bf16 v[16:31], v[142:145], v[146:149], v[16:31]
	v_mfma_f32_32x32x16_bf16 v[0:15], v[142:145], v[150:153], v[0:15]
	s_waitcnt vmcnt(12)
	ds_write_b128 v134, v[80:83] offset:16384
	ds_write_b128 v134, v[84:87] offset:20480
	ds_write_b128 v134, v[88:91] offset:24576
	ds_write_b128 v134, v[92:95] offset:28672
	s_waitcnt lgkmcnt(0)
	s_barrier
	ds_read_b128 v[142:145], v128
	ds_read_b128 v[146:149], v132 offset:16384
	ds_read_b128 v[150:153], v132 offset:20480
	s_waitcnt lgkmcnt(1)
	v_mfma_f32_32x32x16_bf16 v[48:63], v[142:145], v[146:149], v[48:63]
	s_waitcnt lgkmcnt(0)
	v_mfma_f32_32x32x16_bf16 v[32:47], v[142:145], v[150:153], v[32:47]
	ds_read_b128 v[142:145], v128 offset:4096
	s_waitcnt lgkmcnt(0)
	v_mfma_f32_32x32x16_bf16 v[16:31], v[142:145], v[146:149], v[16:31]
	ds_read_b128 v[146:149], v133 offset:16384
	v_mfma_f32_32x32x16_bf16 v[0:15], v[142:145], v[150:153], v[0:15]
	ds_read_b128 v[142:145], v129
	ds_read_b128 v[150:153], v133 offset:20480
	s_waitcnt lgkmcnt(1)
	v_mfma_f32_32x32x16_bf16 v[48:63], v[142:145], v[146:149], v[48:63]
	s_waitcnt lgkmcnt(0)
	v_mfma_f32_32x32x16_bf16 v[32:47], v[142:145], v[150:153], v[32:47]
	ds_read_b128 v[142:145], v129 offset:4096
	s_waitcnt lgkmcnt(0)
	v_mfma_f32_32x32x16_bf16 v[16:31], v[142:145], v[146:149], v[16:31]
	ds_read_b128 v[146:149], v228 offset:16384
	v_mfma_f32_32x32x16_bf16 v[0:15], v[142:145], v[150:153], v[0:15]
	ds_read_b128 v[142:145], v130
	ds_read_b128 v[150:153], v228 offset:20480
	s_waitcnt lgkmcnt(1)
	v_mfma_f32_32x32x16_bf16 v[48:63], v[142:145], v[146:149], v[48:63]
	s_waitcnt lgkmcnt(0)
	v_mfma_f32_32x32x16_bf16 v[32:47], v[142:145], v[150:153], v[32:47]
	ds_read_b128 v[142:145], v130 offset:4096
	s_waitcnt lgkmcnt(0)
	v_mfma_f32_32x32x16_bf16 v[16:31], v[142:145], v[146:149], v[16:31]
	ds_read_b128 v[146:149], v229 offset:16384
	v_mfma_f32_32x32x16_bf16 v[0:15], v[142:145], v[150:153], v[0:15]
	ds_read_b128 v[142:145], v131
	ds_read_b128 v[150:153], v229 offset:20480
	s_waitcnt lgkmcnt(1)
	v_mfma_f32_32x32x16_bf16 v[48:63], v[142:145], v[146:149], v[48:63]
	s_waitcnt lgkmcnt(0)
	v_mfma_f32_32x32x16_bf16 v[32:47], v[142:145], v[150:153], v[32:47]
	ds_read_b128 v[142:145], v131 offset:4096
	s_waitcnt lgkmcnt(0)
	v_mfma_f32_32x32x16_bf16 v[16:31], v[142:145], v[146:149], v[16:31]
	v_mfma_f32_32x32x16_bf16 v[0:15], v[142:145], v[150:153], v[0:15]
	s_waitcnt vmcnt(8)
	ds_write_b128 v134, v[112:115] offset:49152
	ds_write_b128 v134, v[116:119] offset:53248
	ds_write_b128 v134, v[120:123] offset:57344
	ds_write_b128 v134, v[124:127] offset:61440
	s_waitcnt lgkmcnt(0)
	s_barrier
	ds_read_b128 v[142:145], v128 offset:32768
	ds_read_b128 v[146:149], v132 offset:49152
	ds_read_b128 v[150:153], v132 offset:53248
	s_waitcnt lgkmcnt(1)
	v_mfma_f32_32x32x16_bf16 v[48:63], v[142:145], v[146:149], v[48:63]
	s_waitcnt lgkmcnt(0)
	v_mfma_f32_32x32x16_bf16 v[32:47], v[142:145], v[150:153], v[32:47]
	ds_read_b128 v[142:145], v128 offset:36864
	s_waitcnt lgkmcnt(0)
	v_mfma_f32_32x32x16_bf16 v[16:31], v[142:145], v[146:149], v[16:31]
	ds_read_b128 v[146:149], v133 offset:49152
	v_mfma_f32_32x32x16_bf16 v[0:15], v[142:145], v[150:153], v[0:15]
	ds_read_b128 v[142:145], v129 offset:32768
	ds_read_b128 v[150:153], v133 offset:53248
	s_waitcnt lgkmcnt(1)
	v_mfma_f32_32x32x16_bf16 v[48:63], v[142:145], v[146:149], v[48:63]
	s_waitcnt lgkmcnt(0)
	v_mfma_f32_32x32x16_bf16 v[32:47], v[142:145], v[150:153], v[32:47]
	ds_read_b128 v[142:145], v129 offset:36864
	s_waitcnt lgkmcnt(0)
	v_mfma_f32_32x32x16_bf16 v[16:31], v[142:145], v[146:149], v[16:31]
	ds_read_b128 v[146:149], v228 offset:49152
	v_mfma_f32_32x32x16_bf16 v[0:15], v[142:145], v[150:153], v[0:15]
	ds_read_b128 v[142:145], v130 offset:32768
	ds_read_b128 v[150:153], v228 offset:53248
	s_waitcnt lgkmcnt(1)
	v_mfma_f32_32x32x16_bf16 v[48:63], v[142:145], v[146:149], v[48:63]
	s_waitcnt lgkmcnt(0)
	v_mfma_f32_32x32x16_bf16 v[32:47], v[142:145], v[150:153], v[32:47]
	ds_read_b128 v[142:145], v130 offset:36864
	s_waitcnt lgkmcnt(0)
	v_mfma_f32_32x32x16_bf16 v[16:31], v[142:145], v[146:149], v[16:31]
	ds_read_b128 v[146:149], v229 offset:49152
	v_mfma_f32_32x32x16_bf16 v[0:15], v[142:145], v[150:153], v[0:15]
	ds_read_b128 v[142:145], v131 offset:32768
	ds_read_b128 v[150:153], v229 offset:53248
	s_waitcnt lgkmcnt(1)
	v_mfma_f32_32x32x16_bf16 v[48:63], v[142:145], v[146:149], v[48:63]
	s_waitcnt lgkmcnt(0)
	v_mfma_f32_32x32x16_bf16 v[32:47], v[142:145], v[150:153], v[32:47]
	ds_read_b128 v[142:145], v131 offset:36864
	s_waitcnt lgkmcnt(0)
	v_mfma_f32_32x32x16_bf16 v[16:31], v[142:145], v[146:149], v[16:31]
	v_mfma_f32_32x32x16_bf16 v[0:15], v[142:145], v[150:153], v[0:15]
	s_waitcnt vmcnt(4)
	ds_write_b128 v134, v[176:179] offset:16384
	ds_write_b128 v134, v[180:183] offset:20480
	ds_write_b128 v134, v[184:187] offset:24576
	ds_write_b128 v134, v[188:191] offset:28672
	s_waitcnt lgkmcnt(0)
	s_barrier
	ds_read_b128 v[142:145], v128
	ds_read_b128 v[146:149], v132 offset:16384
	ds_read_b128 v[150:153], v132 offset:20480
	s_waitcnt lgkmcnt(1)
	v_mfma_f32_32x32x16_bf16 v[48:63], v[142:145], v[146:149], v[48:63]
	s_waitcnt lgkmcnt(0)
	v_mfma_f32_32x32x16_bf16 v[32:47], v[142:145], v[150:153], v[32:47]
	ds_read_b128 v[142:145], v128 offset:4096
	s_waitcnt lgkmcnt(0)
	v_mfma_f32_32x32x16_bf16 v[16:31], v[142:145], v[146:149], v[16:31]
	ds_read_b128 v[146:149], v133 offset:16384
	v_mfma_f32_32x32x16_bf16 v[0:15], v[142:145], v[150:153], v[0:15]
	ds_read_b128 v[142:145], v129
	ds_read_b128 v[150:153], v133 offset:20480
	s_waitcnt lgkmcnt(1)
	v_mfma_f32_32x32x16_bf16 v[48:63], v[142:145], v[146:149], v[48:63]
	s_waitcnt lgkmcnt(0)
	v_mfma_f32_32x32x16_bf16 v[32:47], v[142:145], v[150:153], v[32:47]
	ds_read_b128 v[142:145], v129 offset:4096
	s_waitcnt lgkmcnt(0)
	v_mfma_f32_32x32x16_bf16 v[16:31], v[142:145], v[146:149], v[16:31]
	ds_read_b128 v[146:149], v228 offset:16384
	v_mfma_f32_32x32x16_bf16 v[0:15], v[142:145], v[150:153], v[0:15]
	ds_read_b128 v[142:145], v130
	ds_read_b128 v[150:153], v228 offset:20480
	s_waitcnt lgkmcnt(1)
	v_mfma_f32_32x32x16_bf16 v[48:63], v[142:145], v[146:149], v[48:63]
	s_waitcnt lgkmcnt(0)
	v_mfma_f32_32x32x16_bf16 v[32:47], v[142:145], v[150:153], v[32:47]
	ds_read_b128 v[142:145], v130 offset:4096
	s_waitcnt lgkmcnt(0)
	v_mfma_f32_32x32x16_bf16 v[16:31], v[142:145], v[146:149], v[16:31]
	ds_read_b128 v[146:149], v229 offset:16384
	v_mfma_f32_32x32x16_bf16 v[0:15], v[142:145], v[150:153], v[0:15]
	ds_read_b128 v[142:145], v131
	ds_read_b128 v[150:153], v229 offset:20480
	s_waitcnt lgkmcnt(1)
	v_mfma_f32_32x32x16_bf16 v[48:63], v[142:145], v[146:149], v[48:63]
	s_waitcnt lgkmcnt(0)
	v_mfma_f32_32x32x16_bf16 v[32:47], v[142:145], v[150:153], v[32:47]
	ds_read_b128 v[142:145], v131 offset:4096
	s_waitcnt lgkmcnt(0)
	v_mfma_f32_32x32x16_bf16 v[16:31], v[142:145], v[146:149], v[16:31]
	v_mfma_f32_32x32x16_bf16 v[0:15], v[142:145], v[150:153], v[0:15]
	s_waitcnt vmcnt(0)
	ds_write_b128 v134, v[212:215] offset:49152
	ds_write_b128 v134, v[216:219] offset:53248
	ds_write_b128 v134, v[220:223] offset:57344
	ds_write_b128 v134, v[224:227] offset:61440
	s_waitcnt lgkmcnt(0)
	s_barrier
	ds_read_b128 v[142:145], v128 offset:32768
	ds_read_b128 v[146:149], v132 offset:49152
	ds_read_b128 v[150:153], v132 offset:53248
	s_waitcnt lgkmcnt(1)
	v_mfma_f32_32x32x16_bf16 v[48:63], v[142:145], v[146:149], v[48:63]
	s_waitcnt lgkmcnt(0)
	v_mfma_f32_32x32x16_bf16 v[32:47], v[142:145], v[150:153], v[32:47]
	ds_read_b128 v[142:145], v128 offset:36864
	s_waitcnt lgkmcnt(0)
	v_mfma_f32_32x32x16_bf16 v[16:31], v[142:145], v[146:149], v[16:31]
	ds_read_b128 v[146:149], v133 offset:49152
	v_mfma_f32_32x32x16_bf16 v[0:15], v[142:145], v[150:153], v[0:15]
	ds_read_b128 v[142:145], v129 offset:32768
	ds_read_b128 v[150:153], v133 offset:53248
	s_waitcnt lgkmcnt(1)
	v_mfma_f32_32x32x16_bf16 v[48:63], v[142:145], v[146:149], v[48:63]
	s_waitcnt lgkmcnt(0)
	v_mfma_f32_32x32x16_bf16 v[32:47], v[142:145], v[150:153], v[32:47]
	ds_read_b128 v[142:145], v129 offset:36864
	s_waitcnt lgkmcnt(0)
	v_mfma_f32_32x32x16_bf16 v[16:31], v[142:145], v[146:149], v[16:31]
	ds_read_b128 v[146:149], v228 offset:49152
	v_mfma_f32_32x32x16_bf16 v[0:15], v[142:145], v[150:153], v[0:15]
	ds_read_b128 v[142:145], v130 offset:32768
	ds_read_b128 v[150:153], v228 offset:53248
	s_waitcnt lgkmcnt(1)
	v_mfma_f32_32x32x16_bf16 v[48:63], v[142:145], v[146:149], v[48:63]
	s_waitcnt lgkmcnt(0)
	v_mfma_f32_32x32x16_bf16 v[32:47], v[142:145], v[150:153], v[32:47]
	ds_read_b128 v[142:145], v130 offset:36864
	s_waitcnt lgkmcnt(0)
	v_mfma_f32_32x32x16_bf16 v[16:31], v[142:145], v[146:149], v[16:31]
	ds_read_b128 v[146:149], v229 offset:49152
	v_mfma_f32_32x32x16_bf16 v[0:15], v[142:145], v[150:153], v[0:15]
	ds_read_b128 v[142:145], v131 offset:32768
	ds_read_b128 v[150:153], v229 offset:53248
	s_waitcnt lgkmcnt(1)
	v_mfma_f32_32x32x16_bf16 v[48:63], v[142:145], v[146:149], v[48:63]
	s_waitcnt lgkmcnt(0)
	v_mfma_f32_32x32x16_bf16 v[32:47], v[142:145], v[150:153], v[32:47]
	ds_read_b128 v[142:145], v131 offset:36864
	s_waitcnt lgkmcnt(0)
	v_mfma_f32_32x32x16_bf16 v[16:31], v[142:145], v[146:149], v[16:31]
	v_mfma_f32_32x32x16_bf16 v[0:15], v[142:145], v[150:153], v[0:15]
	s_barrier
.Lsha_s5y_j:
	s_waitcnt vmcnt(7)
	v_mov_b32_e32 v64, v235
	s_mov_b32 s0, 0x7fffc0
	v_lshrrev_b32_e32 v66, 3, v64
	v_lshrrev_b32_e32 v65, 1, v64
	v_and_b32_e32 v66, 4, v66
	v_and_or_b32 v65, v65, s0, v66
	v_and_b32_e32 v64, 0x5f, v64
	v_lshlrev_b32_e32 v65, 9, v65
	v_lshlrev_b32_e32 v64, 2, v64
	v_add3_u32 v64, s13, v65, v64
	ds_write2_b32 v64, v48, v32 offset1:32
	ds_write2_b32 v64, v49, v33 offset0:128 offset1:160
	v_add_u32_e32 v32, 0x400, v64
	ds_write2_b32 v32, v50, v34 offset1:32
	ds_write2_b32 v32, v51, v35 offset0:128 offset1:160
	v_add_u32_e32 v32, 0x1000, v64
	ds_write2_b32 v32, v52, v36 offset1:32
	ds_write2_b32 v32, v53, v37 offset0:128 offset1:160
	v_add_u32_e32 v32, 0x1400, v64
	ds_write2_b32 v32, v54, v38 offset1:32
	ds_write2_b32 v32, v55, v39 offset0:128 offset1:160
	v_add_u32_e32 v32, 0x2000, v64
	ds_write2_b32 v32, v56, v40 offset1:32
	ds_write2_b32 v32, v57, v41 offset0:128 offset1:160
	v_add_u32_e32 v32, 0x2400, v64
	ds_write2_b32 v32, v58, v42 offset1:32
	ds_write2_b32 v32, v59, v43 offset0:128 offset1:160
	v_add_u32_e32 v32, 0x3000, v64
	ds_write2_b32 v32, v60, v44 offset1:32
	ds_write2_b32 v32, v61, v45 offset0:128 offset1:160
	v_add_u32_e32 v32, 0x3400, v64
	ds_write2_b32 v32, v62, v46 offset1:32
	ds_write2_b32 v32, v63, v47 offset0:128 offset1:160
	v_add_u32_e32 v32, 0x4000, v64
	ds_write2_b32 v32, v16, v0 offset1:32
	ds_write2_b32 v32, v17, v1 offset0:128 offset1:160
	v_add_u32_e32 v0, 0x4400, v64
	ds_write2_b32 v0, v18, v2 offset1:32
	ds_write2_b32 v0, v19, v3 offset0:128 offset1:160
	v_add_u32_e32 v0, 0x5000, v64
	ds_write2_b32 v0, v20, v4 offset1:32
	ds_write2_b32 v0, v21, v5 offset0:128 offset1:160
	v_add_u32_e32 v0, 0x5400, v64
	s_lshl_b32 s0, s2, 5
	ds_write2_b32 v0, v22, v6 offset1:32
	ds_write2_b32 v0, v23, v7 offset0:128 offset1:160
	v_add_u32_e32 v0, 0x6000, v64
	s_add_u32 s0, s60, s0
	ds_write2_b32 v0, v24, v8 offset1:32
	ds_write2_b32 v0, v25, v9 offset0:128 offset1:160
	v_add_u32_e32 v0, 0x6400, v64
	s_mul_i32 s90, s2, 0x3000
	s_addc_u32 s1, s61, 0
	s_lshl_b32 s2, s2, 6
	ds_write2_b32 v0, v26, v10 offset1:32
	ds_write2_b32 v0, v27, v11 offset0:128 offset1:160
	v_add_u32_e32 v0, 0x7000, v64
	s_add_u32 s2, s36, s2
	ds_write2_b32 v0, v28, v12 offset1:32
	ds_write2_b32 v0, v29, v13 offset0:128 offset1:160
	v_add_u32_e32 v0, 0x7400, v64
	s_addc_u32 s3, s37, 0
	s_mov_b32 s40, 0
	ds_write2_b32 v0, v30, v14 offset1:32
	ds_write2_b32 v0, v31, v15 offset0:128 offset1:160
	v_lshlrev_b32_e32 v228, 3, v235
	v_and_b32_e32 v226, 0x78, v228
	v_or_b32_e32 v226, s38, v226
	v_lshrrev_b32_e32 v226, 4, v226
	v_ashrrev_i32_e32 v224, 4, v235
	v_add_u32_e32 v224, s39, v224
	v_lshl_or_b32 v224, v224, 5, v226
	v_ashrrev_i32_e32 v225, 31, v224
	v_lshl_add_u64 v[224:225], s[90:91], 0, v[224:225]
	v_lshlrev_b64 v[224:225], 5, v[224:225]
	v_lshl_add_u64 v[224:225], s[68:69], 0, v[224:225]
	v_and_b32_e32 v228, 8, v228
	v_lshlrev_b32_e32 v226, 1, v228
	v_mov_b32_e32 v227, 0
	v_lshl_add_u64 v[224:225], v[224:225], 0, v[226:227]
	v_lshlrev_b32_e32 v228, 2, v228
	global_load_dwordx4 v[216:219], v228, s[2:3] offset:16
	global_load_dwordx4 v[212:215], v228, s[2:3]
	global_load_dwordx4 v[220:223], v[224:225], off
	s_mov_b32 s14, 0x4000
	s_mov_b32 s15, 0
	s_waitcnt lgkmcnt(0)
	s_barrier
	s_waitcnt vmcnt(0)

.LBB0_763:
	v_readlane_b32 s1, v255, 17
	v_readfirstlane_b32 s0, v234
	s_mul_i32 s1, s39, s1
	v_readlane_b32 s8, v255, 19
	s_lshr_b32 s0, s0, 8
	s_add_i32 s10, s1, s8
	s_add_i32 s10, s10, s0
	s_cmp_gt_u32 s10, 47
	s_mov_b64 s[0:1], -1
	s_cbranch_scc1 .LBB0_762
	s_and_b32 s40, s10, 0xff
	s_mul_i32 s0, s40, 0xab
	s_lshr_b32 s41, s0, 11
	s_mul_i32 s0, s41, 12
	s_sub_i32 s0, s10, s0
	s_and_b32 s0, s0, 0xff
	v_readlane_b32 s1, v255, 36
	s_add_i32 s0, s1, s0
	v_mov_b32_e32 v48, v235
	s_lshl_b32 s0, s0, 17
	s_add_u32 s0, s60, s0
	v_ashrrev_i32_e32 v32, 3, v48
	v_ashrrev_i32_e32 v33, 31, v32
	s_addc_u32 s1, s61, 0
	s_mov_b64 s[24:25], s[0:1]
	s_lshl_b32 s10, s41, 17
	v_lshlrev_b64 v[34:35], 10, v[32:33]
	v_lshlrev_b32_e32 v33, 4, v48
	s_add_u32 s44, s37, s10
	v_lshl_add_u64 v[0:1], s[0:1], 0, v[34:35]
	v_and_b32_e32 v192, 0x70, v33
	v_lshlrev_b32_e32 v230, 10, v32
	v_or_b32_e32 v230, v230, v192
	s_addc_u32 s45, s38, 0
	s_mov_b64 s[72:73], s[44:45]
	v_lshl_add_u64 v[128:129], v[0:1], 0, v[192:193]
	v_lshl_add_u64 v[0:1], s[44:45], 0, v[34:35]
	v_add_co_u32_e32 v36, vcc, s88, v128
	v_lshl_add_u64 v[130:131], v[0:1], 0, v[192:193]
	s_nop 0
	v_addc_co_u32_e32 v37, vcc, 0, v129, vcc
	v_add_co_u32_e32 v38, vcc, s88, v130
	v_addc_co_u32_e32 v39, vcc, 0, v131, vcc
	v_add_co_u32_e32 v40, vcc, s97, v128
	s_nop 0
	v_addc_co_u32_e32 v41, vcc, 0, v129, vcc
	v_add_co_u32_e32 v42, vcc, s97, v130
	s_nop 0
	v_addc_co_u32_e32 v43, vcc, 0, v131, vcc
	v_add_co_u32_e32 v44, vcc, s76, v128
	s_nop 0
	v_addc_co_u32_e32 v45, vcc, 0, v129, vcc
	v_add_co_u32_e32 v46, vcc, s76, v130
	s_nop 0
	v_addc_co_u32_e32 v47, vcc, 0, v131, vcc
	v_and_b32_e32 v49, 31, v48
	v_lshrrev_b32_e32 v52, 1, v48
	s_mov_b32 s0, 0x1ffffc0
	v_lshrrev_b32_e32 v50, 5, v48
	v_bfe_u32 v51, v48, 5, 1
	v_bfe_u32 v53, v48, 1, 3
	v_lshlrev_b32_e32 v54, 7, v48
	v_lshlrev_b32_e32 v32, 7, v32
	v_xor_b32_e32 v33, v33, v48
	v_and_or_b32 v48, v52, s0, v49
	s_movk_i32 s0, 0x70
	v_and_b32_e32 v49, 0x2f80, v54
	v_and_or_b32 v54, v33, s0, v32
	v_add_u32_e32 v138, s36, v54
	v_bitop3_b32 v50, v50, v53, 1 bitop3:0x6c
	v_bitop3_b32 v52, v51, v53, 2 bitop3:0x36
	v_lshl_add_u64 v[32:33], s[60:61], 0, v[34:35]
	s_mov_b32 s43, 0
	v_lshl_add_u32 v134, v48, 7, s36
	v_add_u32_e32 v135, s36, v49
	v_lshlrev_b32_e32 v136, 4, v50
	v_lshlrev_b32_e32 v137, 4, v52
	v_lshl_add_u64 v[132:133], v[32:33], 0, v[192:193]
	v_bitop3_b32 v0, v51, v53, 4 bitop3:0x36
	v_lshlrev_b32_e32 v139, 4, v0
	v_bitop3_b32 v0, v51, v53, 6 bitop3:0x36
	v_lshlrev_b32_e32 v140, 4, v0
	s_add_u32 s30, s24, 0x8000
	s_addc_u32 s31, s25, 0
	s_add_u32 s50, s24, 0x10000
	s_addc_u32 s51, s25, 0
	s_add_u32 s54, s24, 0x18000
	s_addc_u32 s55, s25, 0
	s_add_u32 s74, s72, 0x8000
	s_addc_u32 s75, s73, 0
	s_add_u32 s80, s72, 0x10000
	s_addc_u32 s81, s73, 0
	s_add_u32 s86, s72, 0x18000
	s_addc_u32 s87, s73, 0
	s_cmp_lg_u32 s36, 0
	s_cbranch_scc1 .Lsha_glu_h1
	global_load_dwordx4 v[64:67], v230, s[24:25]
	global_load_dwordx4 v[68:71], v230, s[30:31]
	global_load_dwordx4 v[72:75], v230, s[50:51]
	global_load_dwordx4 v[76:79], v230, s[54:55]
	global_load_dwordx4 v[80:83], v230, s[72:73]
	global_load_dwordx4 v[84:87], v230, s[74:75]
	global_load_dwordx4 v[88:91], v230, s[80:81]
	global_load_dwordx4 v[92:95], v230, s[86:87]
	global_load_dwordx4 v[96:99], v230, s[24:25] offset:128
	global_load_dwordx4 v[100:103], v230, s[30:31] offset:128
	global_load_dwordx4 v[104:107], v230, s[50:51] offset:128
	global_load_dwordx4 v[108:111], v230, s[54:55] offset:128
	global_load_dwordx4 v[112:115], v230, s[72:73] offset:128
	global_load_dwordx4 v[116:119], v230, s[74:75] offset:128
	global_load_dwordx4 v[120:123], v230, s[80:81] offset:128
	global_load_dwordx4 v[124:127], v230, s[86:87] offset:128
	global_load_dwordx4 v[160:163], v230, s[24:25] offset:256
	global_load_dwordx4 v[164:167], v230, s[30:31] offset:256
	global_load_dwordx4 v[168:171], v230, s[50:51] offset:256
	global_load_dwordx4 v[172:175], v230, s[54:55] offset:256
	global_load_dwordx4 v[176:179], v230, s[72:73] offset:256
	global_load_dwordx4 v[180:183], v230, s[74:75] offset:256
	global_load_dwordx4 v[184:187], v230, s[80:81] offset:256
	global_load_dwordx4 v[188:191], v230, s[86:87] offset:256
	global_load_dwordx4 v[196:199], v230, s[24:25] offset:384
	global_load_dwordx4 v[200:203], v230, s[30:31] offset:384
	global_load_dwordx4 v[204:207], v230, s[50:51] offset:384
	global_load_dwordx4 v[208:211], v230, s[54:55] offset:384
	global_load_dwordx4 v[212:215], v230, s[72:73] offset:384
	global_load_dwordx4 v[216:219], v230, s[74:75] offset:384
	global_load_dwordx4 v[220:223], v230, s[80:81] offset:384
	global_load_dwordx4 v[224:227], v230, s[86:87] offset:384
	v_add_u32_e32 v128, v134, v136
	v_add_u32_e32 v132, v135, v136
	v_add_u32_e32 v129, v134, v137
	v_add_u32_e32 v133, v135, v137
	v_add_u32_e32 v130, v134, v139
	v_add_u32_e32 v228, v135, v139
	v_add_u32_e32 v131, v134, v140
	v_add_u32_e32 v229, v135, v140
	v_mov_b32_e32 v0, 0
	v_mov_b32_e32 v1, v0
	v_mov_b32_e32 v2, v0
	v_mov_b32_e32 v3, v0
	v_mov_b32_e32 v4, v0
	v_mov_b32_e32 v5, v0
	v_mov_b32_e32 v6, v0
	v_mov_b32_e32 v7, v0
	v_mov_b32_e32 v8, v0
	v_mov_b32_e32 v9, v0
	v_mov_b32_e32 v10, v0
	v_mov_b32_e32 v11, v0
	v_mov_b32_e32 v12, v0
	v_mov_b32_e32 v13, v0
	v_mov_b32_e32 v14, v0
	v_mov_b32_e32 v15, v0
	v_mov_b32_e32 v16, v0
	v_mov_b32_e32 v17, v0
	v_mov_b32_e32 v18, v0
	v_mov_b32_e32 v19, v0
	v_mov_b32_e32 v20, v0
	v_mov_b32_e32 v21, v0
	v_mov_b32_e32 v22, v0
	v_mov_b32_e32 v23, v0
	v_mov_b32_e32 v24, v0
	v_mov_b32_e32 v25, v0
	v_mov_b32_e32 v26, v0
	v_mov_b32_e32 v27, v0
	v_mov_b32_e32 v28, v0
	v_mov_b32_e32 v29, v0
	v_mov_b32_e32 v30, v0
	v_mov_b32_e32 v31, v0
	v_mov_b32_e32 v32, v0
	v_mov_b32_e32 v33, v0
	v_mov_b32_e32 v34, v0
	v_mov_b32_e32 v35, v0
	v_mov_b32_e32 v36, v0
	v_mov_b32_e32 v37, v0
	v_mov_b32_e32 v38, v0
	v_mov_b32_e32 v39, v0
	v_mov_b32_e32 v40, v0
	v_mov_b32_e32 v41, v0
	v_mov_b32_e32 v42, v0
	v_mov_b32_e32 v43, v0
	v_mov_b32_e32 v44, v0
	v_mov_b32_e32 v45, v0
	v_mov_b32_e32 v46, v0
	v_mov_b32_e32 v47, v0
	v_mov_b32_e32 v48, v0
	v_mov_b32_e32 v49, v0
	v_mov_b32_e32 v50, v0
	v_mov_b32_e32 v51, v0
	v_mov_b32_e32 v52, v0
	v_mov_b32_e32 v53, v0
	v_mov_b32_e32 v54, v0
	v_mov_b32_e32 v55, v0
	v_mov_b32_e32 v56, v0
	v_mov_b32_e32 v57, v0
	v_mov_b32_e32 v58, v0
	v_mov_b32_e32 v59, v0
	v_mov_b32_e32 v60, v0
	v_mov_b32_e32 v61, v0
	v_mov_b32_e32 v62, v0
	v_mov_b32_e32 v63, v0
	s_waitcnt vmcnt(24)
	ds_write_b128 v138, v[64:67]
	ds_write_b128 v138, v[80:83] offset:16384
	ds_write_b128 v138, v[68:71] offset:4096
	ds_write_b128 v138, v[84:87] offset:20480
	ds_write_b128 v138, v[72:75] offset:8192
	ds_write_b128 v138, v[88:91] offset:24576
	ds_write_b128 v138, v[76:79] offset:12288
	ds_write_b128 v138, v[92:95] offset:28672
	s_waitcnt lgkmcnt(0)
	s_barrier
	global_load_dwordx4 v[64:67], v230, s[24:25] offset:512
	global_load_dwordx4 v[68:71], v230, s[30:31] offset:512
	global_load_dwordx4 v[72:75], v230, s[50:51] offset:512
	global_load_dwordx4 v[76:79], v230, s[54:55] offset:512
	global_load_dwordx4 v[80:83], v230, s[72:73] offset:512
	global_load_dwordx4 v[84:87], v230, s[74:75] offset:512
	global_load_dwordx4 v[88:91], v230, s[80:81] offset:512
	global_load_dwordx4 v[92:95], v230, s[86:87] offset:512
	ds_read_b128 v[142:145], v128
	ds_read_b128 v[146:149], v132 offset:16384
	ds_read_b128 v[150:153], v132 offset:20480
	s_waitcnt lgkmcnt(1)
	v_mfma_f32_32x32x16_bf16 v[48:63], v[142:145], v[146:149], v[48:63]
	s_waitcnt lgkmcnt(0)
	v_mfma_f32_32x32x16_bf16 v[32:47], v[142:145], v[150:153], v[32:47]
	ds_read_b128 v[142:145], v128 offset:4096
	s_waitcnt lgkmcnt(0)
	v_mfma_f32_32x32x16_bf16 v[16:31], v[142:145], v[146:149], v[16:31]
	ds_read_b128 v[146:149], v133 offset:16384
	v_mfma_f32_32x32x16_bf16 v[0:15], v[142:145], v[150:153], v[0:15]
	ds_read_b128 v[142:145], v129
	ds_read_b128 v[150:153], v133 offset:20480
	s_waitcnt lgkmcnt(1)
	v_mfma_f32_32x32x16_bf16 v[48:63], v[142:145], v[146:149], v[48:63]
	s_waitcnt lgkmcnt(0)
	v_mfma_f32_32x32x16_bf16 v[32:47], v[142:145], v[150:153], v[32:47]
	ds_read_b128 v[142:145], v129 offset:4096
	s_waitcnt lgkmcnt(0)
	v_mfma_f32_32x32x16_bf16 v[16:31], v[142:145], v[146:149], v[16:31]
	ds_read_b128 v[146:149], v228 offset:16384
	v_mfma_f32_32x32x16_bf16 v[0:15], v[142:145], v[150:153], v[0:15]
	ds_read_b128 v[142:145], v130
	ds_read_b128 v[150:153], v228 offset:20480
	s_waitcnt lgkmcnt(1)
	v_mfma_f32_32x32x16_bf16 v[48:63], v[142:145], v[146:149], v[48:63]
	s_waitcnt lgkmcnt(0)
	v_mfma_f32_32x32x16_bf16 v[32:47], v[142:145], v[150:153], v[32:47]
	ds_read_b128 v[142:145], v130 offset:4096
	s_waitcnt lgkmcnt(0)
	v_mfma_f32_32x32x16_bf16 v[16:31], v[142:145], v[146:149], v[16:31]
	ds_read_b128 v[146:149], v229 offset:16384
	v_mfma_f32_32x32x16_bf16 v[0:15], v[142:145], v[150:153], v[0:15]
	ds_read_b128 v[142:145], v131
	ds_read_b128 v[150:153], v229 offset:20480
	s_waitcnt lgkmcnt(1)
	v_mfma_f32_32x32x16_bf16 v[48:63], v[142:145], v[146:149], v[48:63]
	s_waitcnt lgkmcnt(0)
	v_mfma_f32_32x32x16_bf16 v[32:47], v[142:145], v[150:153], v[32:47]
	ds_read_b128 v[142:145], v131 offset:4096
	s_waitcnt lgkmcnt(0)
	v_mfma_f32_32x32x16_bf16 v[16:31], v[142:145], v[146:149], v[16:31]
	v_mfma_f32_32x32x16_bf16 v[0:15], v[142:145], v[150:153], v[0:15]
	s_waitcnt vmcnt(24)
	ds_write_b128 v138, v[96:99] offset:32768
	ds_write_b128 v138, v[112:115] offset:49152
	ds_write_b128 v138, v[100:103] offset:36864
	ds_write_b128 v138, v[116:119] offset:53248
	ds_write_b128 v138, v[104:107] offset:40960
	ds_write_b128 v138, v[120:123] offset:57344
	ds_write_b128 v138, v[108:111] offset:45056
	ds_write_b128 v138, v[124:127] offset:61440
	s_waitcnt lgkmcnt(0)
	s_barrier
	global_load_dwordx4 v[96:99], v230, s[24:25] offset:640
	global_load_dwordx4 v[100:103], v230, s[30:31] offset:640
	global_load_dwordx4 v[104:107], v230, s[50:51] offset:640
	global_load_dwordx4 v[108:111], v230, s[54:55] offset:640
	global_load_dwordx4 v[112:115], v230, s[72:73] offset:640
	global_load_dwordx4 v[116:119], v230, s[74:75] offset:640
	global_load_dwordx4 v[120:123], v230, s[80:81] offset:640
	global_load_dwordx4 v[124:127], v230, s[86:87] offset:640
	ds_read_b128 v[142:145], v128 offset:32768
	ds_read_b128 v[146:149], v132 offset:49152
	ds_read_b128 v[150:153], v132 offset:53248
	s_waitcnt lgkmcnt(1)
	v_mfma_f32_32x32x16_bf16 v[48:63], v[142:145], v[146:149], v[48:63]
	s_waitcnt lgkmcnt(0)
	v_mfma_f32_32x32x16_bf16 v[32:47], v[142:145], v[150:153], v[32:47]
	ds_read_b128 v[142:145], v128 offset:36864
	s_waitcnt lgkmcnt(0)
	v_mfma_f32_32x32x16_bf16 v[16:31], v[142:145], v[146:149], v[16:31]
	ds_read_b128 v[146:149], v133 offset:49152
	v_mfma_f32_32x32x16_bf16 v[0:15], v[142:145], v[150:153], v[0:15]
	ds_read_b128 v[142:145], v129 offset:32768
	ds_read_b128 v[150:153], v133 offset:53248
	s_waitcnt lgkmcnt(1)
	v_mfma_f32_32x32x16_bf16 v[48:63], v[142:145], v[146:149], v[48:63]
	s_waitcnt lgkmcnt(0)
	v_mfma_f32_32x32x16_bf16 v[32:47], v[142:145], v[150:153], v[32:47]
	ds_read_b128 v[142:145], v129 offset:36864
	s_waitcnt lgkmcnt(0)
	v_mfma_f32_32x32x16_bf16 v[16:31], v[142:145], v[146:149], v[16:31]
	ds_read_b128 v[146:149], v228 offset:49152
	v_mfma_f32_32x32x16_bf16 v[0:15], v[142:145], v[150:153], v[0:15]
	ds_read_b128 v[142:145], v130 offset:32768
	ds_read_b128 v[150:153], v228 offset:53248
	s_waitcnt lgkmcnt(1)
	v_mfma_f32_32x32x16_bf16 v[48:63], v[142:145], v[146:149], v[48:63]
	s_waitcnt lgkmcnt(0)
	v_mfma_f32_32x32x16_bf16 v[32:47], v[142:145], v[150:153], v[32:47]
	ds_read_b128 v[142:145], v130 offset:36864
	s_waitcnt lgkmcnt(0)
	v_mfma_f32_32x32x16_bf16 v[16:31], v[142:145], v[146:149], v[16:31]
	ds_read_b128 v[146:149], v229 offset:49152
	v_mfma_f32_32x32x16_bf16 v[0:15], v[142:145], v[150:153], v[0:15]
	ds_read_b128 v[142:145], v131 offset:32768
	ds_read_b128 v[150:153], v229 offset:53248
	s_waitcnt lgkmcnt(1)
	v_mfma_f32_32x32x16_bf16 v[48:63], v[142:145], v[146:149], v[48:63]
	s_waitcnt lgkmcnt(0)
	v_mfma_f32_32x32x16_bf16 v[32:47], v[142:145], v[150:153], v[32:47]
	ds_read_b128 v[142:145], v131 offset:36864
	s_waitcnt lgkmcnt(0)
	v_mfma_f32_32x32x16_bf16 v[16:31], v[142:145], v[146:149], v[16:31]
	v_mfma_f32_32x32x16_bf16 v[0:15], v[142:145], v[150:153], v[0:15]
	s_waitcnt vmcnt(24)
	ds_write_b128 v138, v[160:163]
	ds_write_b128 v138, v[176:179] offset:16384
	ds_write_b128 v138, v[164:167] offset:4096
	ds_write_b128 v138, v[180:183] offset:20480
	ds_write_b128 v138, v[168:171] offset:8192
	ds_write_b128 v138, v[184:187] offset:24576
	ds_write_b128 v138, v[172:175] offset:12288
	ds_write_b128 v138, v[188:191] offset:28672
	s_waitcnt lgkmcnt(0)
	s_barrier
	global_load_dwordx4 v[160:163], v230, s[24:25] offset:768
	global_load_dwordx4 v[164:167], v230, s[30:31] offset:768
	global_load_dwordx4 v[168:171], v230, s[50:51] offset:768
	global_load_dwordx4 v[172:175], v230, s[54:55] offset:768
	global_load_dwordx4 v[176:179], v230, s[72:73] offset:768
	global_load_dwordx4 v[180:183], v230, s[74:75] offset:768
	global_load_dwordx4 v[184:187], v230, s[80:81] offset:768
	global_load_dwordx4 v[188:191], v230, s[86:87] offset:768
	ds_read_b128 v[142:145], v128
	ds_read_b128 v[146:149], v132 offset:16384
	ds_read_b128 v[150:153], v132 offset:20480
	s_waitcnt lgkmcnt(1)
	v_mfma_f32_32x32x16_bf16 v[48:63], v[142:145], v[146:149], v[48:63]
	s_waitcnt lgkmcnt(0)
	v_mfma_f32_32x32x16_bf16 v[32:47], v[142:145], v[150:153], v[32:47]
	ds_read_b128 v[142:145], v128 offset:4096
	s_waitcnt lgkmcnt(0)
	v_mfma_f32_32x32x16_bf16 v[16:31], v[142:145], v[146:149], v[16:31]
	ds_read_b128 v[146:149], v133 offset:16384
	v_mfma_f32_32x32x16_bf16 v[0:15], v[142:145], v[150:153], v[0:15]
	ds_read_b128 v[142:145], v129
	ds_read_b128 v[150:153], v133 offset:20480
	s_waitcnt lgkmcnt(1)
	v_mfma_f32_32x32x16_bf16 v[48:63], v[142:145], v[146:149], v[48:63]
	s_waitcnt lgkmcnt(0)
	v_mfma_f32_32x32x16_bf16 v[32:47], v[142:145], v[150:153], v[32:47]
	ds_read_b128 v[142:145], v129 offset:4096
	s_waitcnt lgkmcnt(0)
	v_mfma_f32_32x32x16_bf16 v[16:31], v[142:145], v[146:149], v[16:31]
	ds_read_b128 v[146:149], v228 offset:16384
	v_mfma_f32_32x32x16_bf16 v[0:15], v[142:145], v[150:153], v[0:15]
	ds_read_b128 v[142:145], v130
	ds_read_b128 v[150:153], v228 offset:20480
	s_waitcnt lgkmcnt(1)
	v_mfma_f32_32x32x16_bf16 v[48:63], v[142:145], v[146:149], v[48:63]
	s_waitcnt lgkmcnt(0)
	v_mfma_f32_32x32x16_bf16 v[32:47], v[142:145], v[150:153], v[32:47]
	ds_read_b128 v[142:145], v130 offset:4096
	s_waitcnt lgkmcnt(0)
	v_mfma_f32_32x32x16_bf16 v[16:31], v[142:145], v[146:149], v[16:31]
	ds_read_b128 v[146:149], v229 offset:16384
	v_mfma_f32_32x32x16_bf16 v[0:15], v[142:145], v[150:153], v[0:15]
	ds_read_b128 v[142:145], v131
	ds_read_b128 v[150:153], v229 offset:20480
	s_waitcnt lgkmcnt(1)
	v_mfma_f32_32x32x16_bf16 v[48:63], v[142:145], v[146:149], v[48:63]
	s_waitcnt lgkmcnt(0)
	v_mfma_f32_32x32x16_bf16 v[32:47], v[142:145], v[150:153], v[32:47]
	ds_read_b128 v[142:145], v131 offset:4096
	s_waitcnt lgkmcnt(0)
	v_mfma_f32_32x32x16_bf16 v[16:31], v[142:145], v[146:149], v[16:31]
	v_mfma_f32_32x32x16_bf16 v[0:15], v[142:145], v[150:153], v[0:15]
	s_waitcnt vmcnt(24)
	ds_write_b128 v138, v[196:199] offset:32768
	ds_write_b128 v138, v[212:215] offset:49152
	ds_write_b128 v138, v[200:203] offset:36864
	ds_write_b128 v138, v[216:219] offset:53248
	ds_write_b128 v138, v[204:207] offset:40960
	ds_write_b128 v138, v[220:223] offset:57344
	ds_write_b128 v138, v[208:211] offset:45056
	ds_write_b128 v138, v[224:227] offset:61440
	s_waitcnt lgkmcnt(0)
	s_barrier
	global_load_dwordx4 v[196:199], v230, s[24:25] offset:896
	global_load_dwordx4 v[200:203], v230, s[30:31] offset:896
	global_load_dwordx4 v[204:207], v230, s[50:51] offset:896
	global_load_dwordx4 v[208:211], v230, s[54:55] offset:896
	global_load_dwordx4 v[212:215], v230, s[72:73] offset:896
	global_load_dwordx4 v[216:219], v230, s[74:75] offset:896
	global_load_dwordx4 v[220:223], v230, s[80:81] offset:896
	global_load_dwordx4 v[224:227], v230, s[86:87] offset:896
	ds_read_b128 v[142:145], v128 offset:32768
	ds_read_b128 v[146:149], v132 offset:49152
	ds_read_b128 v[150:153], v132 offset:53248
	s_waitcnt lgkmcnt(1)
	v_mfma_f32_32x32x16_bf16 v[48:63], v[142:145], v[146:149], v[48:63]
	s_waitcnt lgkmcnt(0)
	v_mfma_f32_32x32x16_bf16 v[32:47], v[142:145], v[150:153], v[32:47]
	ds_read_b128 v[142:145], v128 offset:36864
	s_waitcnt lgkmcnt(0)
	v_mfma_f32_32x32x16_bf16 v[16:31], v[142:145], v[146:149], v[16:31]
	ds_read_b128 v[146:149], v133 offset:49152
	v_mfma_f32_32x32x16_bf16 v[0:15], v[142:145], v[150:153], v[0:15]
	ds_read_b128 v[142:145], v129 offset:32768
	ds_read_b128 v[150:153], v133 offset:53248
	s_waitcnt lgkmcnt(1)
	v_mfma_f32_32x32x16_bf16 v[48:63], v[142:145], v[146:149], v[48:63]
	s_waitcnt lgkmcnt(0)
	v_mfma_f32_32x32x16_bf16 v[32:47], v[142:145], v[150:153], v[32:47]
	ds_read_b128 v[142:145], v129 offset:36864
	s_waitcnt lgkmcnt(0)
	v_mfma_f32_32x32x16_bf16 v[16:31], v[142:145], v[146:149], v[16:31]
	ds_read_b128 v[146:149], v228 offset:49152
	v_mfma_f32_32x32x16_bf16 v[0:15], v[142:145], v[150:153], v[0:15]
	ds_read_b128 v[142:145], v130 offset:32768
	ds_read_b128 v[150:153], v228 offset:53248
	s_waitcnt lgkmcnt(1)
	v_mfma_f32_32x32x16_bf16 v[48:63], v[142:145], v[146:149], v[48:63]
	s_waitcnt lgkmcnt(0)
	v_mfma_f32_32x32x16_bf16 v[32:47], v[142:145], v[150:153], v[32:47]
	ds_read_b128 v[142:145], v130 offset:36864
	s_waitcnt lgkmcnt(0)
	v_mfma_f32_32x32x16_bf16 v[16:31], v[142:145], v[146:149], v[16:31]
	ds_read_b128 v[146:149], v229 offset:49152
	v_mfma_f32_32x32x16_bf16 v[0:15], v[142:145], v[150:153], v[0:15]
	ds_read_b128 v[142:145], v131 offset:32768
	ds_read_b128 v[150:153], v229 offset:53248
	s_waitcnt lgkmcnt(1)
	v_mfma_f32_32x32x16_bf16 v[48:63], v[142:145], v[146:149], v[48:63]
	s_waitcnt lgkmcnt(0)
	v_mfma_f32_32x32x16_bf16 v[32:47], v[142:145], v[150:153], v[32:47]
	ds_read_b128 v[142:145], v131 offset:36864
	s_waitcnt lgkmcnt(0)
	v_mfma_f32_32x32x16_bf16 v[16:31], v[142:145], v[146:149], v[16:31]
	v_mfma_f32_32x32x16_bf16 v[0:15], v[142:145], v[150:153], v[0:15]
	s_waitcnt vmcnt(24)
	ds_write_b128 v138, v[64:67]
	ds_write_b128 v138, v[80:83] offset:16384
	ds_write_b128 v138, v[68:71] offset:4096
	ds_write_b128 v138, v[84:87] offset:20480
	ds_write_b128 v138, v[72:75] offset:8192
	ds_write_b128 v138, v[88:91] offset:24576
	ds_write_b128 v138, v[76:79] offset:12288
	ds_write_b128 v138, v[92:95] offset:28672
	s_waitcnt lgkmcnt(0)
	s_barrier
	ds_read_b128 v[142:145], v128
	ds_read_b128 v[146:149], v132 offset:16384
	ds_read_b128 v[150:153], v132 offset:20480
	s_waitcnt lgkmcnt(1)
	v_mfma_f32_32x32x16_bf16 v[48:63], v[142:145], v[146:149], v[48:63]
	s_waitcnt lgkmcnt(0)
	v_mfma_f32_32x32x16_bf16 v[32:47], v[142:145], v[150:153], v[32:47]
	ds_read_b128 v[142:145], v128 offset:4096
	s_waitcnt lgkmcnt(0)
	v_mfma_f32_32x32x16_bf16 v[16:31], v[142:145], v[146:149], v[16:31]
	ds_read_b128 v[146:149], v133 offset:16384
	v_mfma_f32_32x32x16_bf16 v[0:15], v[142:145], v[150:153], v[0:15]
	ds_read_b128 v[142:145], v129
	ds_read_b128 v[150:153], v133 offset:20480
	s_waitcnt lgkmcnt(1)
	v_mfma_f32_32x32x16_bf16 v[48:63], v[142:145], v[146:149], v[48:63]
	s_waitcnt lgkmcnt(0)
	v_mfma_f32_32x32x16_bf16 v[32:47], v[142:145], v[150:153], v[32:47]
	ds_read_b128 v[142:145], v129 offset:4096
	s_waitcnt lgkmcnt(0)
	v_mfma_f32_32x32x16_bf16 v[16:31], v[142:145], v[146:149], v[16:31]
	ds_read_b128 v[146:149], v228 offset:16384
	v_mfma_f32_32x32x16_bf16 v[0:15], v[142:145], v[150:153], v[0:15]
	ds_read_b128 v[142:145], v130
	ds_read_b128 v[150:153], v228 offset:20480
	s_waitcnt lgkmcnt(1)
	v_mfma_f32_32x32x16_bf16 v[48:63], v[142:145], v[146:149], v[48:63]
	s_waitcnt lgkmcnt(0)
	v_mfma_f32_32x32x16_bf16 v[32:47], v[142:145], v[150:153], v[32:47]
	ds_read_b128 v[142:145], v130 offset:4096
	s_waitcnt lgkmcnt(0)
	v_mfma_f32_32x32x16_bf16 v[16:31], v[142:145], v[146:149], v[16:31]
	ds_read_b128 v[146:149], v229 offset:16384
	v_mfma_f32_32x32x16_bf16 v[0:15], v[142:145], v[150:153], v[0:15]
	ds_read_b128 v[142:145], v131
	ds_read_b128 v[150:153], v229 offset:20480
	s_waitcnt lgkmcnt(1)
	v_mfma_f32_32x32x16_bf16 v[48:63], v[142:145], v[146:149], v[48:63]
	s_waitcnt lgkmcnt(0)
	v_mfma_f32_32x32x16_bf16 v[32:47], v[142:145], v[150:153], v[32:47]
	ds_read_b128 v[142:145], v131 offset:4096
	s_waitcnt lgkmcnt(0)
	v_mfma_f32_32x32x16_bf16 v[16:31], v[142:145], v[146:149], v[16:31]
	v_mfma_f32_32x32x16_bf16 v[0:15], v[142:145], v[150:153], v[0:15]
	s_waitcnt vmcnt(16)
	ds_write_b128 v138, v[96:99] offset:32768
	ds_write_b128 v138, v[112:115] offset:49152
	ds_write_b128 v138, v[100:103] offset:36864
	ds_write_b128 v138, v[116:119] offset:53248
	ds_write_b128 v138, v[104:107] offset:40960
	ds_write_b128 v138, v[120:123] offset:57344
	ds_write_b128 v138, v[108:111] offset:45056
	ds_write_b128 v138, v[124:127] offset:61440
	s_waitcnt lgkmcnt(0)
	s_barrier
	ds_read_b128 v[142:145], v128 offset:32768
	ds_read_b128 v[146:149], v132 offset:49152
	ds_read_b128 v[150:153], v132 offset:53248
	s_waitcnt lgkmcnt(1)
	v_mfma_f32_32x32x16_bf16 v[48:63], v[142:145], v[146:149], v[48:63]
	s_waitcnt lgkmcnt(0)
	v_mfma_f32_32x32x16_bf16 v[32:47], v[142:145], v[150:153], v[32:47]
	ds_read_b128 v[142:145], v128 offset:36864
	s_waitcnt lgkmcnt(0)
	v_mfma_f32_32x32x16_bf16 v[16:31], v[142:145], v[146:149], v[16:31]
	ds_read_b128 v[146:149], v133 offset:49152
	v_mfma_f32_32x32x16_bf16 v[0:15], v[142:145], v[150:153], v[0:15]
	ds_read_b128 v[142:145], v129 offset:32768
	ds_read_b128 v[150:153], v133 offset:53248
	s_waitcnt lgkmcnt(1)
	v_mfma_f32_32x32x16_bf16 v[48:63], v[142:145], v[146:149], v[48:63]
	s_waitcnt lgkmcnt(0)
	v_mfma_f32_32x32x16_bf16 v[32:47], v[142:145], v[150:153], v[32:47]
	ds_read_b128 v[142:145], v129 offset:36864
	s_waitcnt lgkmcnt(0)
	v_mfma_f32_32x32x16_bf16 v[16:31], v[142:145], v[146:149], v[16:31]
	ds_read_b128 v[146:149], v228 offset:49152
	v_mfma_f32_32x32x16_bf16 v[0:15], v[142:145], v[150:153], v[0:15]
	ds_read_b128 v[142:145], v130 offset:32768
	ds_read_b128 v[150:153], v228 offset:53248
	s_waitcnt lgkmcnt(1)
	v_mfma_f32_32x32x16_bf16 v[48:63], v[142:145], v[146:149], v[48:63]
	s_waitcnt lgkmcnt(0)
	v_mfma_f32_32x32x16_bf16 v[32:47], v[142:145], v[150:153], v[32:47]
	ds_read_b128 v[142:145], v130 offset:36864
	s_waitcnt lgkmcnt(0)
	v_mfma_f32_32x32x16_bf16 v[16:31], v[142:145], v[146:149], v[16:31]
	ds_read_b128 v[146:149], v229 offset:49152
	v_mfma_f32_32x32x16_bf16 v[0:15], v[142:145], v[150:153], v[0:15]
	ds_read_b128 v[142:145], v131 offset:32768
	ds_read_b128 v[150:153], v229 offset:53248
	s_waitcnt lgkmcnt(1)
	v_mfma_f32_32x32x16_bf16 v[48:63], v[142:145], v[146:149], v[48:63]
	s_waitcnt lgkmcnt(0)
	v_mfma_f32_32x32x16_bf16 v[32:47], v[142:145], v[150:153], v[32:47]
	ds_read_b128 v[142:145], v131 offset:36864
	s_waitcnt lgkmcnt(0)
	v_mfma_f32_32x32x16_bf16 v[16:31], v[142:145], v[146:149], v[16:31]
	v_mfma_f32_32x32x16_bf16 v[0:15], v[142:145], v[150:153], v[0:15]
	s_waitcnt vmcnt(8)
	ds_write_b128 v138, v[160:163]
	ds_write_b128 v138, v[176:179] offset:16384
	ds_write_b128 v138, v[164:167] offset:4096
	ds_write_b128 v138, v[180:183] offset:20480
	ds_write_b128 v138, v[168:171] offset:8192
	ds_write_b128 v138, v[184:187] offset:24576
	ds_write_b128 v138, v[172:175] offset:12288
	ds_write_b128 v138, v[188:191] offset:28672
	s_waitcnt lgkmcnt(0)
	s_barrier
	ds_read_b128 v[142:145], v128
	ds_read_b128 v[146:149], v132 offset:16384
	ds_read_b128 v[150:153], v132 offset:20480
	s_waitcnt lgkmcnt(1)
	v_mfma_f32_32x32x16_bf16 v[48:63], v[142:145], v[146:149], v[48:63]
	s_waitcnt lgkmcnt(0)
	v_mfma_f32_32x32x16_bf16 v[32:47], v[142:145], v[150:153], v[32:47]
	ds_read_b128 v[142:145], v128 offset:4096
	s_waitcnt lgkmcnt(0)
	v_mfma_f32_32x32x16_bf16 v[16:31], v[142:145], v[146:149], v[16:31]
	ds_read_b128 v[146:149], v133 offset:16384
	v_mfma_f32_32x32x16_bf16 v[0:15], v[142:145], v[150:153], v[0:15]
	ds_read_b128 v[142:145], v129
	ds_read_b128 v[150:153], v133 offset:20480
	s_waitcnt lgkmcnt(1)
	v_mfma_f32_32x32x16_bf16 v[48:63], v[142:145], v[146:149], v[48:63]
	s_waitcnt lgkmcnt(0)
	v_mfma_f32_32x32x16_bf16 v[32:47], v[142:145], v[150:153], v[32:47]
	ds_read_b128 v[142:145], v129 offset:4096
	s_waitcnt lgkmcnt(0)
	v_mfma_f32_32x32x16_bf16 v[16:31], v[142:145], v[146:149], v[16:31]
	ds_read_b128 v[146:149], v228 offset:16384
	v_mfma_f32_32x32x16_bf16 v[0:15], v[142:145], v[150:153], v[0:15]
	ds_read_b128 v[142:145], v130
	ds_read_b128 v[150:153], v228 offset:20480
	s_waitcnt lgkmcnt(1)
	v_mfma_f32_32x32x16_bf16 v[48:63], v[142:145], v[146:149], v[48:63]
	s_waitcnt lgkmcnt(0)
	v_mfma_f32_32x32x16_bf16 v[32:47], v[142:145], v[150:153], v[32:47]
	ds_read_b128 v[142:145], v130 offset:4096
	s_waitcnt lgkmcnt(0)
	v_mfma_f32_32x32x16_bf16 v[16:31], v[142:145], v[146:149], v[16:31]
	ds_read_b128 v[146:149], v229 offset:16384
	v_mfma_f32_32x32x16_bf16 v[0:15], v[142:145], v[150:153], v[0:15]
	ds_read_b128 v[142:145], v131
	ds_read_b128 v[150:153], v229 offset:20480
	s_waitcnt lgkmcnt(1)
	v_mfma_f32_32x32x16_bf16 v[48:63], v[142:145], v[146:149], v[48:63]
	s_waitcnt lgkmcnt(0)
	v_mfma_f32_32x32x16_bf16 v[32:47], v[142:145], v[150:153], v[32:47]
	ds_read_b128 v[142:145], v131 offset:4096
	s_waitcnt lgkmcnt(0)
	v_mfma_f32_32x32x16_bf16 v[16:31], v[142:145], v[146:149], v[16:31]
	v_mfma_f32_32x32x16_bf16 v[0:15], v[142:145], v[150:153], v[0:15]
	s_waitcnt vmcnt(0)
	ds_write_b128 v138, v[196:199] offset:32768
	ds_write_b128 v138, v[212:215] offset:49152
	ds_write_b128 v138, v[200:203] offset:36864
	ds_write_b128 v138, v[216:219] offset:53248
	ds_write_b128 v138, v[204:207] offset:40960
	ds_write_b128 v138, v[220:223] offset:57344
	ds_write_b128 v138, v[208:211] offset:45056
	ds_write_b128 v138, v[224:227] offset:61440
	s_waitcnt lgkmcnt(0)
	s_barrier
	ds_read_b128 v[142:145], v128 offset:32768
	ds_read_b128 v[146:149], v132 offset:49152
	ds_read_b128 v[150:153], v132 offset:53248
	s_waitcnt lgkmcnt(1)
	v_mfma_f32_32x32x16_bf16 v[48:63], v[142:145], v[146:149], v[48:63]
	s_waitcnt lgkmcnt(0)
	v_mfma_f32_32x32x16_bf16 v[32:47], v[142:145], v[150:153], v[32:47]
	ds_read_b128 v[142:145], v128 offset:36864
	s_waitcnt lgkmcnt(0)
	v_mfma_f32_32x32x16_bf16 v[16:31], v[142:145], v[146:149], v[16:31]
	ds_read_b128 v[146:149], v133 offset:49152
	v_mfma_f32_32x32x16_bf16 v[0:15], v[142:145], v[150:153], v[0:15]
	ds_read_b128 v[142:145], v129 offset:32768
	ds_read_b128 v[150:153], v133 offset:53248
	s_waitcnt lgkmcnt(1)
	v_mfma_f32_32x32x16_bf16 v[48:63], v[142:145], v[146:149], v[48:63]
	s_waitcnt lgkmcnt(0)
	v_mfma_f32_32x32x16_bf16 v[32:47], v[142:145], v[150:153], v[32:47]
	ds_read_b128 v[142:145], v129 offset:36864
	s_waitcnt lgkmcnt(0)
	v_mfma_f32_32x32x16_bf16 v[16:31], v[142:145], v[146:149], v[16:31]
	ds_read_b128 v[146:149], v228 offset:49152
	v_mfma_f32_32x32x16_bf16 v[0:15], v[142:145], v[150:153], v[0:15]
	ds_read_b128 v[142:145], v130 offset:32768
	ds_read_b128 v[150:153], v228 offset:53248
	s_waitcnt lgkmcnt(1)
	v_mfma_f32_32x32x16_bf16 v[48:63], v[142:145], v[146:149], v[48:63]
	s_waitcnt lgkmcnt(0)
	v_mfma_f32_32x32x16_bf16 v[32:47], v[142:145], v[150:153], v[32:47]
	ds_read_b128 v[142:145], v130 offset:36864
	s_waitcnt lgkmcnt(0)
	v_mfma_f32_32x32x16_bf16 v[16:31], v[142:145], v[146:149], v[16:31]
	ds_read_b128 v[146:149], v229 offset:49152
	v_mfma_f32_32x32x16_bf16 v[0:15], v[142:145], v[150:153], v[0:15]
	ds_read_b128 v[142:145], v131 offset:32768
	ds_read_b128 v[150:153], v229 offset:53248
	s_waitcnt lgkmcnt(1)
	v_mfma_f32_32x32x16_bf16 v[48:63], v[142:145], v[146:149], v[48:63]
	s_waitcnt lgkmcnt(0)
	v_mfma_f32_32x32x16_bf16 v[32:47], v[142:145], v[150:153], v[32:47]
	ds_read_b128 v[142:145], v131 offset:36864
	s_waitcnt lgkmcnt(0)
	v_mfma_f32_32x32x16_bf16 v[16:31], v[142:145], v[146:149], v[16:31]
	v_mfma_f32_32x32x16_bf16 v[0:15], v[142:145], v[150:153], v[0:15]
	s_barrier
	s_branch .Lsha_glu_j
.Lsha_glu_h1:
	global_load_dwordx4 v[64:67], v230, s[24:25]
	global_load_dwordx4 v[68:71], v230, s[30:31]
	global_load_dwordx4 v[72:75], v230, s[50:51]
	global_load_dwordx4 v[76:79], v230, s[54:55]
	global_load_dwordx4 v[96:99], v230, s[24:25] offset:128
	global_load_dwordx4 v[100:103], v230, s[30:31] offset:128
	global_load_dwordx4 v[104:107], v230, s[50:51] offset:128
	global_load_dwordx4 v[108:111], v230, s[54:55] offset:128
	global_load_dwordx4 v[160:163], v230, s[24:25] offset:256
	global_load_dwordx4 v[164:167], v230, s[30:31] offset:256
	global_load_dwordx4 v[168:171], v230, s[50:51] offset:256
	global_load_dwordx4 v[172:175], v230, s[54:55] offset:256
	global_load_dwordx4 v[196:199], v230, s[24:25] offset:384
	global_load_dwordx4 v[200:203], v230, s[30:31] offset:384
	global_load_dwordx4 v[204:207], v230, s[50:51] offset:384
	global_load_dwordx4 v[208:211], v230, s[54:55] offset:384
	v_add_u32_e32 v128, v134, v136
	v_add_u32_e32 v132, v135, v136
	v_add_u32_e32 v129, v134, v137
	v_add_u32_e32 v133, v135, v137
	v_add_u32_e32 v130, v134, v139
	v_add_u32_e32 v228, v135, v139
	v_add_u32_e32 v131, v134, v140
	v_add_u32_e32 v229, v135, v140
	v_add_u32_e32 v132, 0xffff0000, v132
	v_add_u32_e32 v133, 0xffff0000, v133
	v_add_u32_e32 v228, 0xffff0000, v228
	v_add_u32_e32 v229, 0xffff0000, v229
	v_mov_b32_e32 v0, 0
	v_mov_b32_e32 v1, v0
	v_mov_b32_e32 v2, v0
	v_mov_b32_e32 v3, v0
	v_mov_b32_e32 v4, v0
	v_mov_b32_e32 v5, v0
	v_mov_b32_e32 v6, v0
	v_mov_b32_e32 v7, v0
	v_mov_b32_e32 v8, v0
	v_mov_b32_e32 v9, v0
	v_mov_b32_e32 v10, v0
	v_mov_b32_e32 v11, v0
	v_mov_b32_e32 v12, v0
	v_mov_b32_e32 v13, v0
	v_mov_b32_e32 v14, v0
	v_mov_b32_e32 v15, v0
	v_mov_b32_e32 v16, v0
	v_mov_b32_e32 v17, v0
	v_mov_b32_e32 v18, v0
	v_mov_b32_e32 v19, v0
	v_mov_b32_e32 v20, v0
	v_mov_b32_e32 v21, v0
	v_mov_b32_e32 v22, v0
	v_mov_b32_e32 v23, v0
	v_mov_b32_e32 v24, v0
	v_mov_b32_e32 v25, v0
	v_mov_b32_e32 v26, v0
	v_mov_b32_e32 v27, v0
	v_mov_b32_e32 v28, v0
	v_mov_b32_e32 v29, v0
	v_mov_b32_e32 v30, v0
	v_mov_b32_e32 v31, v0
	v_mov_b32_e32 v32, v0
	v_mov_b32_e32 v33, v0
	v_mov_b32_e32 v34, v0
	v_mov_b32_e32 v35, v0
	v_mov_b32_e32 v36, v0
	v_mov_b32_e32 v37, v0
	v_mov_b32_e32 v38, v0
	v_mov_b32_e32 v39, v0
	v_mov_b32_e32 v40, v0
	v_mov_b32_e32 v41, v0
	v_mov_b32_e32 v42, v0
	v_mov_b32_e32 v43, v0
	v_mov_b32_e32 v44, v0
	v_mov_b32_e32 v45, v0
	v_mov_b32_e32 v46, v0
	v_mov_b32_e32 v47, v0
	v_mov_b32_e32 v48, v0
	v_mov_b32_e32 v49, v0
	v_mov_b32_e32 v50, v0
	v_mov_b32_e32 v51, v0
	v_mov_b32_e32 v52, v0
	v_mov_b32_e32 v53, v0
	v_mov_b32_e32 v54, v0
	v_mov_b32_e32 v55, v0
	v_mov_b32_e32 v56, v0
	v_mov_b32_e32 v57, v0
	v_mov_b32_e32 v58, v0
	v_mov_b32_e32 v59, v0
	v_mov_b32_e32 v60, v0
	v_mov_b32_e32 v61, v0
	v_mov_b32_e32 v62, v0
	v_mov_b32_e32 v63, v0
	s_waitcnt vmcnt(12)
	ds_write_b128 v138, v[64:67]
	ds_write_b128 v138, v[68:71] offset:4096
	ds_write_b128 v138, v[72:75] offset:8192
	ds_write_b128 v138, v[76:79] offset:12288
	s_waitcnt lgkmcnt(0)
	s_barrier
	global_load_dwordx4 v[64:67], v230, s[24:25] offset:512
	global_load_dwordx4 v[68:71], v230, s[30:31] offset:512
	global_load_dwordx4 v[72:75], v230, s[50:51] offset:512
	global_load_dwordx4 v[76:79], v230, s[54:55] offset:512
	ds_read_b128 v[142:145], v128
	ds_read_b128 v[146:149], v132 offset:16384
	ds_read_b128 v[150:153], v132 offset:20480
	s_waitcnt lgkmcnt(1)
	v_mfma_f32_32x32x16_bf16 v[48:63], v[142:145], v[146:149], v[48:63]
	s_waitcnt lgkmcnt(0)
	v_mfma_f32_32x32x16_bf16 v[32:47], v[142:145], v[150:153], v[32:47]
	ds_read_b128 v[142:145], v128 offset:4096
	s_waitcnt lgkmcnt(0)
	v_mfma_f32_32x32x16_bf16 v[16:31], v[142:145], v[146:149], v[16:31]
	ds_read_b128 v[146:149], v133 offset:16384
	v_mfma_f32_32x32x16_bf16 v[0:15], v[142:145], v[150:153], v[0:15]
	ds_read_b128 v[142:145], v129
	ds_read_b128 v[150:153], v133 offset:20480
	s_waitcnt lgkmcnt(1)
	v_mfma_f32_32x32x16_bf16 v[48:63], v[142:145], v[146:149], v[48:63]
	s_waitcnt lgkmcnt(0)
	v_mfma_f32_32x32x16_bf16 v[32:47], v[142:145], v[150:153], v[32:47]
	ds_read_b128 v[142:145], v129 offset:4096
	s_waitcnt lgkmcnt(0)
	v_mfma_f32_32x32x16_bf16 v[16:31], v[142:145], v[146:149], v[16:31]
	ds_read_b128 v[146:149], v228 offset:16384
	v_mfma_f32_32x32x16_bf16 v[0:15], v[142:145], v[150:153], v[0:15]
	ds_read_b128 v[142:145], v130
	ds_read_b128 v[150:153], v228 offset:20480
	s_waitcnt lgkmcnt(1)
	v_mfma_f32_32x32x16_bf16 v[48:63], v[142:145], v[146:149], v[48:63]
	s_waitcnt lgkmcnt(0)
	v_mfma_f32_32x32x16_bf16 v[32:47], v[142:145], v[150:153], v[32:47]
	ds_read_b128 v[142:145], v130 offset:4096
	s_waitcnt lgkmcnt(0)
	v_mfma_f32_32x32x16_bf16 v[16:31], v[142:145], v[146:149], v[16:31]
	ds_read_b128 v[146:149], v229 offset:16384
	v_mfma_f32_32x32x16_bf16 v[0:15], v[142:145], v[150:153], v[0:15]
	ds_read_b128 v[142:145], v131
	ds_read_b128 v[150:153], v229 offset:20480
	s_waitcnt lgkmcnt(1)
	v_mfma_f32_32x32x16_bf16 v[48:63], v[142:145], v[146:149], v[48:63]
	s_waitcnt lgkmcnt(0)
	v_mfma_f32_32x32x16_bf16 v[32:47], v[142:145], v[150:153], v[32:47]
	ds_read_b128 v[142:145], v131 offset:4096
	s_waitcnt lgkmcnt(0)
	v_mfma_f32_32x32x16_bf16 v[16:31], v[142:145], v[146:149], v[16:31]
	v_mfma_f32_32x32x16_bf16 v[0:15], v[142:145], v[150:153], v[0:15]
	s_waitcnt vmcnt(12)
	ds_write_b128 v138, v[96:99] offset:32768
	ds_write_b128 v138, v[100:103] offset:36864
	ds_write_b128 v138, v[104:107] offset:40960
	ds_write_b128 v138, v[108:111] offset:45056
	s_waitcnt lgkmcnt(0)
	s_barrier
	global_load_dwordx4 v[96:99], v230, s[24:25] offset:640
	global_load_dwordx4 v[100:103], v230, s[30:31] offset:640
	global_load_dwordx4 v[104:107], v230, s[50:51] offset:640
	global_load_dwordx4 v[108:111], v230, s[54:55] offset:640
	ds_read_b128 v[142:145], v128 offset:32768
	ds_read_b128 v[146:149], v132 offset:49152
	ds_read_b128 v[150:153], v132 offset:53248
	s_waitcnt lgkmcnt(1)
	v_mfma_f32_32x32x16_bf16 v[48:63], v[142:145], v[146:149], v[48:63]
	s_waitcnt lgkmcnt(0)
	v_mfma_f32_32x32x16_bf16 v[32:47], v[142:145], v[150:153], v[32:47]
	ds_read_b128 v[142:145], v128 offset:36864
	s_waitcnt lgkmcnt(0)
	v_mfma_f32_32x32x16_bf16 v[16:31], v[142:145], v[146:149], v[16:31]
	ds_read_b128 v[146:149], v133 offset:49152
	v_mfma_f32_32x32x16_bf16 v[0:15], v[142:145], v[150:153], v[0:15]
	ds_read_b128 v[142:145], v129 offset:32768
	ds_read_b128 v[150:153], v133 offset:53248
	s_waitcnt lgkmcnt(1)
	v_mfma_f32_32x32x16_bf16 v[48:63], v[142:145], v[146:149], v[48:63]
	s_waitcnt lgkmcnt(0)
	v_mfma_f32_32x32x16_bf16 v[32:47], v[142:145], v[150:153], v[32:47]
	ds_read_b128 v[142:145], v129 offset:36864
	s_waitcnt lgkmcnt(0)
	v_mfma_f32_32x32x16_bf16 v[16:31], v[142:145], v[146:149], v[16:31]
	ds_read_b128 v[146:149], v228 offset:49152
	v_mfma_f32_32x32x16_bf16 v[0:15], v[142:145], v[150:153], v[0:15]
	ds_read_b128 v[142:145], v130 offset:32768
	ds_read_b128 v[150:153], v228 offset:53248
	s_waitcnt lgkmcnt(1)
	v_mfma_f32_32x32x16_bf16 v[48:63], v[142:145], v[146:149], v[48:63]
	s_waitcnt lgkmcnt(0)
	v_mfma_f32_32x32x16_bf16 v[32:47], v[142:145], v[150:153], v[32:47]
	ds_read_b128 v[142:145], v130 offset:36864
	s_waitcnt lgkmcnt(0)
	v_mfma_f32_32x32x16_bf16 v[16:31], v[142:145], v[146:149], v[16:31]
	ds_read_b128 v[146:149], v229 offset:49152
	v_mfma_f32_32x32x16_bf16 v[0:15], v[142:145], v[150:153], v[0:15]
	ds_read_b128 v[142:145], v131 offset:32768
	ds_read_b128 v[150:153], v229 offset:53248
	s_waitcnt lgkmcnt(1)
	v_mfma_f32_32x32x16_bf16 v[48:63], v[142:145], v[146:149], v[48:63]
	s_waitcnt lgkmcnt(0)
	v_mfma_f32_32x32x16_bf16 v[32:47], v[142:145], v[150:153], v[32:47]
	ds_read_b128 v[142:145], v131 offset:36864
	s_waitcnt lgkmcnt(0)
	v_mfma_f32_32x32x16_bf16 v[16:31], v[142:145], v[146:149], v[16:31]
	v_mfma_f32_32x32x16_bf16 v[0:15], v[142:145], v[150:153], v[0:15]
	s_waitcnt vmcnt(12)
	ds_write_b128 v138, v[160:163]
	ds_write_b128 v138, v[164:167] offset:4096
	ds_write_b128 v138, v[168:171] offset:8192
	ds_write_b128 v138, v[172:175] offset:12288
	s_waitcnt lgkmcnt(0)
	s_barrier
	global_load_dwordx4 v[160:163], v230, s[24:25] offset:768
	global_load_dwordx4 v[164:167], v230, s[30:31] offset:768
	global_load_dwordx4 v[168:171], v230, s[50:51] offset:768
	global_load_dwordx4 v[172:175], v230, s[54:55] offset:768
	ds_read_b128 v[142:145], v128
	ds_read_b128 v[146:149], v132 offset:16384
	ds_read_b128 v[150:153], v132 offset:20480
	s_waitcnt lgkmcnt(1)
	v_mfma_f32_32x32x16_bf16 v[48:63], v[142:145], v[146:149], v[48:63]
	s_waitcnt lgkmcnt(0)
	v_mfma_f32_32x32x16_bf16 v[32:47], v[142:145], v[150:153], v[32:47]
	ds_read_b128 v[142:145], v128 offset:4096
	s_waitcnt lgkmcnt(0)
	v_mfma_f32_32x32x16_bf16 v[16:31], v[142:145], v[146:149], v[16:31]
	ds_read_b128 v[146:149], v133 offset:16384
	v_mfma_f32_32x32x16_bf16 v[0:15], v[142:145], v[150:153], v[0:15]
	ds_read_b128 v[142:145], v129
	ds_read_b128 v[150:153], v133 offset:20480
	s_waitcnt lgkmcnt(1)
	v_mfma_f32_32x32x16_bf16 v[48:63], v[142:145], v[146:149], v[48:63]
	s_waitcnt lgkmcnt(0)
	v_mfma_f32_32x32x16_bf16 v[32:47], v[142:145], v[150:153], v[32:47]
	ds_read_b128 v[142:145], v129 offset:4096
	s_waitcnt lgkmcnt(0)
	v_mfma_f32_32x32x16_bf16 v[16:31], v[142:145], v[146:149], v[16:31]
	ds_read_b128 v[146:149], v228 offset:16384
	v_mfma_f32_32x32x16_bf16 v[0:15], v[142:145], v[150:153], v[0:15]
	ds_read_b128 v[142:145], v130
	ds_read_b128 v[150:153], v228 offset:20480
	s_waitcnt lgkmcnt(1)
	v_mfma_f32_32x32x16_bf16 v[48:63], v[142:145], v[146:149], v[48:63]
	s_waitcnt lgkmcnt(0)
	v_mfma_f32_32x32x16_bf16 v[32:47], v[142:145], v[150:153], v[32:47]
	ds_read_b128 v[142:145], v130 offset:4096
	s_waitcnt lgkmcnt(0)
	v_mfma_f32_32x32x16_bf16 v[16:31], v[142:145], v[146:149], v[16:31]
	ds_read_b128 v[146:149], v229 offset:16384
	v_mfma_f32_32x32x16_bf16 v[0:15], v[142:145], v[150:153], v[0:15]
	ds_read_b128 v[142:145], v131
	ds_read_b128 v[150:153], v229 offset:20480
	s_waitcnt lgkmcnt(1)
	v_mfma_f32_32x32x16_bf16 v[48:63], v[142:145], v[146:149], v[48:63]
	s_waitcnt lgkmcnt(0)
	v_mfma_f32_32x32x16_bf16 v[32:47], v[142:145], v[150:153], v[32:47]
	ds_read_b128 v[142:145], v131 offset:4096
	s_waitcnt lgkmcnt(0)
	v_mfma_f32_32x32x16_bf16 v[16:31], v[142:145], v[146:149], v[16:31]
	v_mfma_f32_32x32x16_bf16 v[0:15], v[142:145], v[150:153], v[0:15]
	s_waitcnt vmcnt(12)
	ds_write_b128 v138, v[196:199] offset:32768
	ds_write_b128 v138, v[200:203] offset:36864
	ds_write_b128 v138, v[204:207] offset:40960
	ds_write_b128 v138, v[208:211] offset:45056
	s_waitcnt lgkmcnt(0)
	s_barrier
	global_load_dwordx4 v[196:199], v230, s[24:25] offset:896
	global_load_dwordx4 v[200:203], v230, s[30:31] offset:896
	global_load_dwordx4 v[204:207], v230, s[50:51] offset:896
	global_load_dwordx4 v[208:211], v230, s[54:55] offset:896
	ds_read_b128 v[142:145], v128 offset:32768
	ds_read_b128 v[146:149], v132 offset:49152
	ds_read_b128 v[150:153], v132 offset:53248
	s_waitcnt lgkmcnt(1)
	v_mfma_f32_32x32x16_bf16 v[48:63], v[142:145], v[146:149], v[48:63]
	s_waitcnt lgkmcnt(0)
	v_mfma_f32_32x32x16_bf16 v[32:47], v[142:145], v[150:153], v[32:47]
	ds_read_b128 v[142:145], v128 offset:36864
	s_waitcnt lgkmcnt(0)
	v_mfma_f32_32x32x16_bf16 v[16:31], v[142:145], v[146:149], v[16:31]
	ds_read_b128 v[146:149], v133 offset:49152
	v_mfma_f32_32x32x16_bf16 v[0:15], v[142:145], v[150:153], v[0:15]
	ds_read_b128 v[142:145], v129 offset:32768
	ds_read_b128 v[150:153], v133 offset:53248
	s_waitcnt lgkmcnt(1)
	v_mfma_f32_32x32x16_bf16 v[48:63], v[142:145], v[146:149], v[48:63]
	s_waitcnt lgkmcnt(0)
	v_mfma_f32_32x32x16_bf16 v[32:47], v[142:145], v[150:153], v[32:47]
	ds_read_b128 v[142:145], v129 offset:36864
	s_waitcnt lgkmcnt(0)
	v_mfma_f32_32x32x16_bf16 v[16:31], v[142:145], v[146:149], v[16:31]
	ds_read_b128 v[146:149], v228 offset:49152
	v_mfma_f32_32x32x16_bf16 v[0:15], v[142:145], v[150:153], v[0:15]
	ds_read_b128 v[142:145], v130 offset:32768
	ds_read_b128 v[150:153], v228 offset:53248
	s_waitcnt lgkmcnt(1)
	v_mfma_f32_32x32x16_bf16 v[48:63], v[142:145], v[146:149], v[48:63]
	s_waitcnt lgkmcnt(0)
	v_mfma_f32_32x32x16_bf16 v[32:47], v[142:145], v[150:153], v[32:47]
	ds_read_b128 v[142:145], v130 offset:36864
	s_waitcnt lgkmcnt(0)
	v_mfma_f32_32x32x16_bf16 v[16:31], v[142:145], v[146:149], v[16:31]
	ds_read_b128 v[146:149], v229 offset:49152
	v_mfma_f32_32x32x16_bf16 v[0:15], v[142:145], v[150:153], v[0:15]
	ds_read_b128 v[142:145], v131 offset:32768
	ds_read_b128 v[150:153], v229 offset:53248
	s_waitcnt lgkmcnt(1)
	v_mfma_f32_32x32x16_bf16 v[48:63], v[142:145], v[146:149], v[48:63]
	s_waitcnt lgkmcnt(0)
	v_mfma_f32_32x32x16_bf16 v[32:47], v[142:145], v[150:153], v[32:47]
	ds_read_b128 v[142:145], v131 offset:36864
	s_waitcnt lgkmcnt(0)
	v_mfma_f32_32x32x16_bf16 v[16:31], v[142:145], v[146:149], v[16:31]
	v_mfma_f32_32x32x16_bf16 v[0:15], v[142:145], v[150:153], v[0:15]
	s_waitcnt vmcnt(12)
	ds_write_b128 v138, v[64:67]
	ds_write_b128 v138, v[68:71] offset:4096
	ds_write_b128 v138, v[72:75] offset:8192
	ds_write_b128 v138, v[76:79] offset:12288
	s_waitcnt lgkmcnt(0)
	s_barrier
	ds_read_b128 v[142:145], v128
	ds_read_b128 v[146:149], v132 offset:16384
	ds_read_b128 v[150:153], v132 offset:20480
	s_waitcnt lgkmcnt(1)
	v_mfma_f32_32x32x16_bf16 v[48:63], v[142:145], v[146:149], v[48:63]
	s_waitcnt lgkmcnt(0)
	v_mfma_f32_32x32x16_bf16 v[32:47], v[142:145], v[150:153], v[32:47]
	ds_read_b128 v[142:145], v128 offset:4096
	s_waitcnt lgkmcnt(0)
	v_mfma_f32_32x32x16_bf16 v[16:31], v[142:145], v[146:149], v[16:31]
	ds_read_b128 v[146:149], v133 offset:16384
	v_mfma_f32_32x32x16_bf16 v[0:15], v[142:145], v[150:153], v[0:15]
	ds_read_b128 v[142:145], v129
	ds_read_b128 v[150:153], v133 offset:20480
	s_waitcnt lgkmcnt(1)
	v_mfma_f32_32x32x16_bf16 v[48:63], v[142:145], v[146:149], v[48:63]
	s_waitcnt lgkmcnt(0)
	v_mfma_f32_32x32x16_bf16 v[32:47], v[142:145], v[150:153], v[32:47]
	ds_read_b128 v[142:145], v129 offset:4096
	s_waitcnt lgkmcnt(0)
	v_mfma_f32_32x32x16_bf16 v[16:31], v[142:145], v[146:149], v[16:31]
	ds_read_b128 v[146:149], v228 offset:16384
	v_mfma_f32_32x32x16_bf16 v[0:15], v[142:145], v[150:153], v[0:15]
	ds_read_b128 v[142:145], v130
	ds_read_b128 v[150:153], v228 offset:20480
	s_waitcnt lgkmcnt(1)
	v_mfma_f32_32x32x16_bf16 v[48:63], v[142:145], v[146:149], v[48:63]
	s_waitcnt lgkmcnt(0)
	v_mfma_f32_32x32x16_bf16 v[32:47], v[142:145], v[150:153], v[32:47]
	ds_read_b128 v[142:145], v130 offset:4096
	s_waitcnt lgkmcnt(0)
	v_mfma_f32_32x32x16_bf16 v[16:31], v[142:145], v[146:149], v[16:31]
	ds_read_b128 v[146:149], v229 offset:16384
	v_mfma_f32_32x32x16_bf16 v[0:15], v[142:145], v[150:153], v[0:15]
	ds_read_b128 v[142:145], v131
	ds_read_b128 v[150:153], v229 offset:20480
	s_waitcnt lgkmcnt(1)
	v_mfma_f32_32x32x16_bf16 v[48:63], v[142:145], v[146:149], v[48:63]
	s_waitcnt lgkmcnt(0)
	v_mfma_f32_32x32x16_bf16 v[32:47], v[142:145], v[150:153], v[32:47]
	ds_read_b128 v[142:145], v131 offset:4096
	s_waitcnt lgkmcnt(0)
	v_mfma_f32_32x32x16_bf16 v[16:31], v[142:145], v[146:149], v[16:31]
	v_mfma_f32_32x32x16_bf16 v[0:15], v[142:145], v[150:153], v[0:15]
	s_waitcnt vmcnt(8)
	ds_write_b128 v138, v[96:99] offset:32768
	ds_write_b128 v138, v[100:103] offset:36864
	ds_write_b128 v138, v[104:107] offset:40960
	ds_write_b128 v138, v[108:111] offset:45056
	s_waitcnt lgkmcnt(0)
	s_barrier
	ds_read_b128 v[142:145], v128 offset:32768
	ds_read_b128 v[146:149], v132 offset:49152
	ds_read_b128 v[150:153], v132 offset:53248
	s_waitcnt lgkmcnt(1)
	v_mfma_f32_32x32x16_bf16 v[48:63], v[142:145], v[146:149], v[48:63]
	s_waitcnt lgkmcnt(0)
	v_mfma_f32_32x32x16_bf16 v[32:47], v[142:145], v[150:153], v[32:47]
	ds_read_b128 v[142:145], v128 offset:36864
	s_waitcnt lgkmcnt(0)
	v_mfma_f32_32x32x16_bf16 v[16:31], v[142:145], v[146:149], v[16:31]
	ds_read_b128 v[146:149], v133 offset:49152
	v_mfma_f32_32x32x16_bf16 v[0:15], v[142:145], v[150:153], v[0:15]
	ds_read_b128 v[142:145], v129 offset:32768
	ds_read_b128 v[150:153], v133 offset:53248
	s_waitcnt lgkmcnt(1)
	v_mfma_f32_32x32x16_bf16 v[48:63], v[142:145], v[146:149], v[48:63]
	s_waitcnt lgkmcnt(0)
	v_mfma_f32_32x32x16_bf16 v[32:47], v[142:145], v[150:153], v[32:47]
	ds_read_b128 v[142:145], v129 offset:36864
	s_waitcnt lgkmcnt(0)
	v_mfma_f32_32x32x16_bf16 v[16:31], v[142:145], v[146:149], v[16:31]
	ds_read_b128 v[146:149], v228 offset:49152
	v_mfma_f32_32x32x16_bf16 v[0:15], v[142:145], v[150:153], v[0:15]
	ds_read_b128 v[142:145], v130 offset:32768
	ds_read_b128 v[150:153], v228 offset:53248
	s_waitcnt lgkmcnt(1)
	v_mfma_f32_32x32x16_bf16 v[48:63], v[142:145], v[146:149], v[48:63]
	s_waitcnt lgkmcnt(0)
	v_mfma_f32_32x32x16_bf16 v[32:47], v[142:145], v[150:153], v[32:47]
	ds_read_b128 v[142:145], v130 offset:36864
	s_waitcnt lgkmcnt(0)
	v_mfma_f32_32x32x16_bf16 v[16:31], v[142:145], v[146:149], v[16:31]
	ds_read_b128 v[146:149], v229 offset:49152
	v_mfma_f32_32x32x16_bf16 v[0:15], v[142:145], v[150:153], v[0:15]
	ds_read_b128 v[142:145], v131 offset:32768
	ds_read_b128 v[150:153], v229 offset:53248
	s_waitcnt lgkmcnt(1)
	v_mfma_f32_32x32x16_bf16 v[48:63], v[142:145], v[146:149], v[48:63]
	s_waitcnt lgkmcnt(0)
	v_mfma_f32_32x32x16_bf16 v[32:47], v[142:145], v[150:153], v[32:47]
	ds_read_b128 v[142:145], v131 offset:36864
	s_waitcnt lgkmcnt(0)
	v_mfma_f32_32x32x16_bf16 v[16:31], v[142:145], v[146:149], v[16:31]
	v_mfma_f32_32x32x16_bf16 v[0:15], v[142:145], v[150:153], v[0:15]
	s_waitcnt vmcnt(4)
	ds_write_b128 v138, v[160:163]
	ds_write_b128 v138, v[164:167] offset:4096
	ds_write_b128 v138, v[168:171] offset:8192
	ds_write_b128 v138, v[172:175] offset:12288
	s_waitcnt lgkmcnt(0)
	s_barrier
	ds_read_b128 v[142:145], v128
	ds_read_b128 v[146:149], v132 offset:16384
	ds_read_b128 v[150:153], v132 offset:20480
	s_waitcnt lgkmcnt(1)
	v_mfma_f32_32x32x16_bf16 v[48:63], v[142:145], v[146:149], v[48:63]
	s_waitcnt lgkmcnt(0)
	v_mfma_f32_32x32x16_bf16 v[32:47], v[142:145], v[150:153], v[32:47]
	ds_read_b128 v[142:145], v128 offset:4096
	s_waitcnt lgkmcnt(0)
	v_mfma_f32_32x32x16_bf16 v[16:31], v[142:145], v[146:149], v[16:31]
	ds_read_b128 v[146:149], v133 offset:16384
	v_mfma_f32_32x32x16_bf16 v[0:15], v[142:145], v[150:153], v[0:15]
	ds_read_b128 v[142:145], v129
	ds_read_b128 v[150:153], v133 offset:20480
	s_waitcnt lgkmcnt(1)
	v_mfma_f32_32x32x16_bf16 v[48:63], v[142:145], v[146:149], v[48:63]
	s_waitcnt lgkmcnt(0)
	v_mfma_f32_32x32x16_bf16 v[32:47], v[142:145], v[150:153], v[32:47]
	ds_read_b128 v[142:145], v129 offset:4096
	s_waitcnt lgkmcnt(0)
	v_mfma_f32_32x32x16_bf16 v[16:31], v[142:145], v[146:149], v[16:31]
	ds_read_b128 v[146:149], v228 offset:16384
	v_mfma_f32_32x32x16_bf16 v[0:15], v[142:145], v[150:153], v[0:15]
	ds_read_b128 v[142:145], v130
	ds_read_b128 v[150:153], v228 offset:20480
	s_waitcnt lgkmcnt(1)
	v_mfma_f32_32x32x16_bf16 v[48:63], v[142:145], v[146:149], v[48:63]
	s_waitcnt lgkmcnt(0)
	v_mfma_f32_32x32x16_bf16 v[32:47], v[142:145], v[150:153], v[32:47]
	ds_read_b128 v[142:145], v130 offset:4096
	s_waitcnt lgkmcnt(0)
	v_mfma_f32_32x32x16_bf16 v[16:31], v[142:145], v[146:149], v[16:31]
	ds_read_b128 v[146:149], v229 offset:16384
	v_mfma_f32_32x32x16_bf16 v[0:15], v[142:145], v[150:153], v[0:15]
	ds_read_b128 v[142:145], v131
	ds_read_b128 v[150:153], v229 offset:20480
	s_waitcnt lgkmcnt(1)
	v_mfma_f32_32x32x16_bf16 v[48:63], v[142:145], v[146:149], v[48:63]
	s_waitcnt lgkmcnt(0)
	v_mfma_f32_32x32x16_bf16 v[32:47], v[142:145], v[150:153], v[32:47]
	ds_read_b128 v[142:145], v131 offset:4096
	s_waitcnt lgkmcnt(0)
	v_mfma_f32_32x32x16_bf16 v[16:31], v[142:145], v[146:149], v[16:31]
	v_mfma_f32_32x32x16_bf16 v[0:15], v[142:145], v[150:153], v[0:15]
	s_waitcnt vmcnt(0)
	ds_write_b128 v138, v[196:199] offset:32768
	ds_write_b128 v138, v[200:203] offset:36864
	ds_write_b128 v138, v[204:207] offset:40960
	ds_write_b128 v138, v[208:211] offset:45056
	s_waitcnt lgkmcnt(0)
	s_barrier
	ds_read_b128 v[142:145], v128 offset:32768
	ds_read_b128 v[146:149], v132 offset:49152
	ds_read_b128 v[150:153], v132 offset:53248
	s_waitcnt lgkmcnt(1)
	v_mfma_f32_32x32x16_bf16 v[48:63], v[142:145], v[146:149], v[48:63]
	s_waitcnt lgkmcnt(0)
	v_mfma_f32_32x32x16_bf16 v[32:47], v[142:145], v[150:153], v[32:47]
	ds_read_b128 v[142:145], v128 offset:36864
	s_waitcnt lgkmcnt(0)
	v_mfma_f32_32x32x16_bf16 v[16:31], v[142:145], v[146:149], v[16:31]
	ds_read_b128 v[146:149], v133 offset:49152
	v_mfma_f32_32x32x16_bf16 v[0:15], v[142:145], v[150:153], v[0:15]
	ds_read_b128 v[142:145], v129 offset:32768
	ds_read_b128 v[150:153], v133 offset:53248
	s_waitcnt lgkmcnt(1)
	v_mfma_f32_32x32x16_bf16 v[48:63], v[142:145], v[146:149], v[48:63]
	s_waitcnt lgkmcnt(0)
	v_mfma_f32_32x32x16_bf16 v[32:47], v[142:145], v[150:153], v[32:47]
	ds_read_b128 v[142:145], v129 offset:36864
	s_waitcnt lgkmcnt(0)
	v_mfma_f32_32x32x16_bf16 v[16:31], v[142:145], v[146:149], v[16:31]
	ds_read_b128 v[146:149], v228 offset:49152
	v_mfma_f32_32x32x16_bf16 v[0:15], v[142:145], v[150:153], v[0:15]
	ds_read_b128 v[142:145], v130 offset:32768
	ds_read_b128 v[150:153], v228 offset:53248
	s_waitcnt lgkmcnt(1)
	v_mfma_f32_32x32x16_bf16 v[48:63], v[142:145], v[146:149], v[48:63]
	s_waitcnt lgkmcnt(0)
	v_mfma_f32_32x32x16_bf16 v[32:47], v[142:145], v[150:153], v[32:47]
	ds_read_b128 v[142:145], v130 offset:36864
	s_waitcnt lgkmcnt(0)
	v_mfma_f32_32x32x16_bf16 v[16:31], v[142:145], v[146:149], v[16:31]
	ds_read_b128 v[146:149], v229 offset:49152
	v_mfma_f32_32x32x16_bf16 v[0:15], v[142:145], v[150:153], v[0:15]
	ds_read_b128 v[142:145], v131 offset:32768
	ds_read_b128 v[150:153], v229 offset:53248
	s_waitcnt lgkmcnt(1)
	v_mfma_f32_32x32x16_bf16 v[48:63], v[142:145], v[146:149], v[48:63]
	s_waitcnt lgkmcnt(0)
	v_mfma_f32_32x32x16_bf16 v[32:47], v[142:145], v[150:153], v[32:47]
	ds_read_b128 v[142:145], v131 offset:36864
	s_waitcnt lgkmcnt(0)
	v_mfma_f32_32x32x16_bf16 v[16:31], v[142:145], v[146:149], v[16:31]
	v_mfma_f32_32x32x16_bf16 v[0:15], v[142:145], v[150:153], v[0:15]
	s_barrier
.Lsha_glu_j:
	s_waitcnt vmcnt(7)
	v_mov_b32_e32 v64, v235
	s_mov_b32 s1, 0x7fffc0
	v_lshrrev_b32_e32 v66, 3, v64
	v_lshrrev_b32_e32 v65, 1, v64
	v_and_b32_e32 v66, 4, v66
	v_and_or_b32 v65, v65, s1, v66
	v_and_b32_e32 v64, 0x5f, v64
	v_lshlrev_b32_e32 v65, 9, v65
	v_lshlrev_b32_e32 v64, 2, v64
	v_add3_u32 v64, s36, v65, v64
	ds_write2_b32 v64, v48, v32 offset1:32
	ds_write2_b32 v64, v49, v33 offset0:128 offset1:160
	v_add_u32_e32 v32, 0x400, v64
	ds_write2_b32 v32, v50, v34 offset1:32
	ds_write2_b32 v32, v51, v35 offset0:128 offset1:160
	v_add_u32_e32 v32, 0x1000, v64
	ds_write2_b32 v32, v52, v36 offset1:32
	ds_write2_b32 v32, v53, v37 offset0:128 offset1:160
	v_add_u32_e32 v32, 0x1400, v64
	ds_write2_b32 v32, v54, v38 offset1:32
	ds_write2_b32 v32, v55, v39 offset0:128 offset1:160
	v_add_u32_e32 v32, 0x2000, v64
	ds_write2_b32 v32, v56, v40 offset1:32
	ds_write2_b32 v32, v57, v41 offset0:128 offset1:160
	v_add_u32_e32 v32, 0x2400, v64
	ds_write2_b32 v32, v58, v42 offset1:32
	ds_write2_b32 v32, v59, v43 offset0:128 offset1:160
	v_add_u32_e32 v32, 0x3000, v64
	ds_write2_b32 v32, v60, v44 offset1:32
	ds_write2_b32 v32, v61, v45 offset0:128 offset1:160
	v_add_u32_e32 v32, 0x3400, v64
	ds_write2_b32 v32, v62, v46 offset1:32
	ds_write2_b32 v32, v63, v47 offset0:128 offset1:160
	v_add_u32_e32 v32, 0x4000, v64
	ds_write2_b32 v32, v16, v0 offset1:32
	ds_write2_b32 v32, v17, v1 offset0:128 offset1:160
	v_add_u32_e32 v0, 0x4400, v64
	ds_write2_b32 v0, v18, v2 offset1:32
	ds_write2_b32 v0, v19, v3 offset0:128 offset1:160
	v_add_u32_e32 v0, 0x5000, v64
	ds_write2_b32 v0, v20, v4 offset1:32
	ds_write2_b32 v0, v21, v5 offset0:128 offset1:160
	v_add_u32_e32 v0, 0x5400, v64
	ds_write2_b32 v0, v22, v6 offset1:32
	ds_write2_b32 v0, v23, v7 offset0:128 offset1:160
	v_add_u32_e32 v0, 0x6000, v64
	ds_write2_b32 v0, v24, v8 offset1:32
	ds_write2_b32 v0, v25, v9 offset0:128 offset1:160
	v_add_u32_e32 v0, 0x6400, v64
	s_lshl_b32 s1, s40, 7
	v_readlane_b32 s8, v255, 37
	s_mul_hi_u32 s10, s40, 0x15555556
	s_and_b32 s0, 0xffff, s41
	ds_write2_b32 v0, v26, v10 offset1:32
	ds_write2_b32 v0, v27, v11 offset0:128 offset1:160
	v_add_u32_e32 v0, 0x7000, v64
	s_add_i32 s1, s8, s1
	s_mulk_i32 s10, 0x600
	s_lshl_b32 s0, s0, 7
	ds_write2_b32 v0, v28, v12 offset1:32
	ds_write2_b32 v0, v29, v13 offset0:128 offset1:160
	v_add_u32_e32 v0, 0x7400, v64
	s_sub_i32 s1, s1, s10
	s_mov_b32 s10, 0
	ds_write2_b32 v0, v30, v14 offset1:32
	ds_write2_b32 v0, v31, v15 offset0:128 offset1:160
	v_lshlrev_b32_e32 v232, 3, v235
	v_and_b32_e32 v232, 0x78, v232
	v_or_b32_e32 v232, s0, v232
	v_ashrrev_i32_e32 v233, 4, v235
	v_add_u32_e32 v233, s1, v233
	v_mov_b64_e32 v[224:225], s[58:59]
	v_mad_i64_i32 v[224:225], s[46:47], v233, s94, v[224:225]
	v_ashrrev_i32_e32 v227, 31, v233
	v_mov_b32_e32 v226, v233
	v_lshlrev_b64 v[226:227], 10, v[226:227]
	v_lshl_add_u64 v[226:227], s[60:61], 0, v[226:227]
	v_lshlrev_b32_e32 v233, 1, v232
	v_mov_b32_e32 v229, 0
	v_mov_b32_e32 v228, v233
	v_lshl_add_u64 v[224:225], v[224:225], 0, v[228:229]
	v_lshl_add_u64 v[226:227], v[226:227], 0, v[228:229]
	v_lshlrev_b32_e32 v232, 2, v232
	global_load_dwordx4 v[212:215], v232, s[12:13]
	global_load_dwordx4 v[228:231], v232, s[12:13] offset:16
	global_load_dwordx4 v[216:219], v[224:225], off
	global_load_dwordx4 v[220:223], v[226:227], off
	s_mov_b32 s46, 0x20200
	s_mov_b32 s47, 0
	s_mov_b32 s48, 0x4000
	s_mov_b32 s49, 0
	s_waitcnt lgkmcnt(0)
	s_barrier
	s_waitcnt vmcnt(0)
